# grid-barrier poll loops: s_sleep 1 replaced by s_nop 0 (tighter polling)
# baseline (speedup 1.0000x reference)
; __global__ void __launch_bounds__(NWAVES * 64, 2) mk_fwd(Args args) {
;     ...
;     if (args.ws == nullptr) grid.sync();
.LBB0_127:
	s_nop 0
	global_load_dword v2, v0, s[8:9] offset:32 sc1
	s_waitcnt vmcnt(0)
	v_and_b32_e32 v2, 0xffff0000, v2
	v_cmp_ne_u32_e32 vcc, v2, v1
	s_or_b64 s[10:11], vcc, s[10:11]
	s_andn2_b64 exec, exec, s[10:11]
	s_cbranch_execnz .LBB0_127

; __device__ __forceinline__ unsigned xb_ld(unsigned* p)              { return __hip_atomic_load(p, __ATOMIC_RELAXED, __HIP_MEMORY_SCOPE_AGENT); }
; __device__ __forceinline__ void xcd_barrier_complete(unsigned* bar, unsigned x, unsigned& nloc, unsigned& nx) {
;     ...
;     for (;;) {
;         sum = 0u; cnt = 0u; mine = 0u;
; #pragma unroll
;         for (unsigned j = 0; j < 16; ++j) { const unsigned c = xb_ld(&bar[XB_XCNT(j)]); sum += c; cnt += (c > 0u) ? 1u : 0u; mine = (j == x) ? c : mine; }
;         if (sum == G) break;
;         __builtin_amdgcn_s_sleep(1);
;         if ((++sp & 255u) == 0u) { if (xb_ld(&bar[XB_TMO])) break; if (sp > XB_SPIN_CAP) { atomicAdd(&bar[XB_TMO], 1u); break; } }
;     }
.LBB0_134:
	global_load_dword v15, v16, s[10:11] sc1
	s_waitcnt lgkmcnt(0)
	global_load_dword v0, v16, s[12:13] sc1
	global_load_dword v1, v16, s[16:17] sc1
	global_load_dword v2, v16, s[20:21] sc1
	global_load_dword v3, v16, s[24:25] sc1
	global_load_dword v4, v16, s[26:27] sc1
	global_load_dword v5, v16, s[28:29] sc1
	global_load_dword v6, v16, s[40:41] sc1
	global_load_dword v7, v16, s[42:43] sc1
	global_load_dword v8, v16, s[44:45] sc1
	global_load_dword v9, v16, s[48:49] sc1
	global_load_dword v10, v16, s[50:51] sc1
	global_load_dword v11, v16, s[54:55] sc1
	global_load_dword v12, v16, s[56:57] sc1
	global_load_dword v13, v16, s[58:59] sc1
	global_load_dword v14, v16, s[60:61] sc1
	s_mov_b64 s[62:63], -1
	s_mov_b64 s[64:65], -1
	s_waitcnt vmcnt(14)
	v_add_u32_e32 v17, v0, v15
	s_waitcnt vmcnt(13)
	v_add_u32_e32 v17, v17, v1
	s_waitcnt vmcnt(12)
	v_add_u32_e32 v17, v17, v2
	s_waitcnt vmcnt(11)
	v_add_u32_e32 v17, v17, v3
	s_waitcnt vmcnt(10)
	v_add_u32_e32 v17, v17, v4
	s_waitcnt vmcnt(9)
	v_add_u32_e32 v17, v17, v5
	s_waitcnt vmcnt(8)
	v_add_u32_e32 v17, v17, v6
	s_waitcnt vmcnt(7)
	v_add_u32_e32 v17, v17, v7
	s_waitcnt vmcnt(6)
	v_add_u32_e32 v17, v17, v8
	s_waitcnt vmcnt(5)
	v_add_u32_e32 v17, v17, v9
	s_waitcnt vmcnt(4)
	v_add_u32_e32 v17, v17, v10
	s_waitcnt vmcnt(3)
	v_add_u32_e32 v17, v17, v11
	s_waitcnt vmcnt(2)
	v_add_u32_e32 v17, v17, v12
	s_waitcnt vmcnt(1)
	v_add_u32_e32 v17, v17, v13
	s_waitcnt vmcnt(0)
	v_add_u32_e32 v17, v17, v14
	v_cmp_eq_u32_e32 vcc, s3, v17
	s_cbranch_vccnz .LBB0_133
	s_and_b32 s15, s14, 0xff
	s_cmp_eq_u32 s15, 0
	s_mov_b64 s[66:67], -1
	s_nop 0
	s_cbranch_scc0 .LBB0_138
	global_load_dword v17, v16, s[8:9] sc1
	s_waitcnt vmcnt(0)
	v_cmp_eq_u32_e32 vcc, 0, v17
	s_cbranch_vccnz .LBB0_140
	s_mov_b64 s[66:67], 0

; __device__ __forceinline__ unsigned xb_ld(unsigned* p)              { return __hip_atomic_load(p, __ATOMIC_RELAXED, __HIP_MEMORY_SCOPE_AGENT); }
; #define XB_SPIN(cond, bar) do { unsigned _sp = 0; while (cond) { __builtin_amdgcn_s_sleep(1); \
;     if ((++_sp & 255u) == 0u) { if (xb_ld(&(bar)[XB_TMO])) break; if (_sp > XB_SPIN_CAP) { atomicAdd(&(bar)[XB_TMO], 1u); break; } } } } while (0)
; __device__ __forceinline__ void xcd_barrier(const XcdBarrier& b) {
;     ...
;             else XB_SPIN(xb_ld(&bar[XB_TOPGEN]) == tg, bar);
.LBB0_152:
	s_and_b32 s14, s3, 0xff
	s_mov_b64 s[28:29], -1
	s_cmp_lg_u32 s14, 0
	s_mov_b64 s[42:43], -1
	s_nop 0
	s_cbranch_scc1 .LBB0_155
	global_load_dword v2, v0, s[16:17] sc1
	s_waitcnt vmcnt(0)
	v_cmp_eq_u32_e32 vcc, 0, v2
	s_cbranch_vccnz .LBB0_157
	s_mov_b64 s[42:43], 0
	s_mov_b64 s[40:41], -1

; __device__ __forceinline__ unsigned xb_ld(unsigned* p)              { return __hip_atomic_load(p, __ATOMIC_RELAXED, __HIP_MEMORY_SCOPE_AGENT); }
; #define XB_SPIN(cond, bar) do { unsigned _sp = 0; while (cond) { __builtin_amdgcn_s_sleep(1); \
;     if ((++_sp & 255u) == 0u) { if (xb_ld(&(bar)[XB_TMO])) break; if (_sp > XB_SPIN_CAP) { atomicAdd(&(bar)[XB_TMO], 1u); break; } } } } while (0)
; __device__ __forceinline__ void xcd_barrier(const XcdBarrier& b) {
;     ...
;             XB_SPIN(xb_ld(&bar[XB_XGEN(b.x)]) == gen, bar);
.LBB0_169:
	s_and_b32 s14, s3, 0xff
	s_cmp_lg_u32 s14, 0
	s_mov_b64 s[40:41], -1
	s_nop 0
	s_cbranch_scc1 .LBB0_172
	global_load_dword v1, v0, s[16:17] sc1
	s_waitcnt vmcnt(0)
	v_cmp_eq_u32_e32 vcc, 0, v1
	s_cbranch_vccnz .LBB0_174
	s_mov_b64 s[40:41], 0
	s_mov_b64 s[28:29], -1

; __device__ __forceinline__ unsigned xb_ld(unsigned* p)              { return __hip_atomic_load(p, __ATOMIC_RELAXED, __HIP_MEMORY_SCOPE_AGENT); }
; __device__ __forceinline__ void xcd_barrier_complete(unsigned* bar, unsigned x, unsigned& nloc, unsigned& nx) {
;     ...
;     for (;;) {
;         sum = 0u; cnt = 0u; mine = 0u;
; #pragma unroll
;         for (unsigned j = 0; j < 16; ++j) { const unsigned c = xb_ld(&bar[XB_XCNT(j)]); sum += c; cnt += (c > 0u) ? 1u : 0u; mine = (j == x) ? c : mine; }
;         if (sum == G) break;
;         __builtin_amdgcn_s_sleep(1);
;         if ((++sp & 255u) == 0u) { if (xb_ld(&bar[XB_TMO])) break; if (sp > XB_SPIN_CAP) { atomicAdd(&bar[XB_TMO], 1u); break; } }
;     }
.LBB0_202:
	global_load_dword v15, v16, s[8:9] sc1
	global_load_dword v0, v16, s[10:11] sc1
	global_load_dword v1, v16, s[16:17] sc1
	global_load_dword v2, v16, s[24:25] sc1
	global_load_dword v3, v16, s[26:27] sc1
	global_load_dword v4, v16, s[28:29] sc1
	global_load_dword v5, v16, s[40:41] sc1
	global_load_dword v6, v16, s[44:45] sc1
	global_load_dword v7, v16, s[48:49] sc1
	global_load_dword v8, v16, s[50:51] sc1
	global_load_dword v9, v16, s[54:55] sc1
	global_load_dword v10, v16, s[56:57] sc1
	global_load_dword v11, v16, s[58:59] sc1
	global_load_dword v12, v16, s[60:61] sc1
	global_load_dword v13, v16, s[62:63] sc1
	global_load_dword v14, v16, s[64:65] sc1
	s_mov_b64 s[66:67], -1
	s_mov_b64 s[86:87], -1
	s_waitcnt vmcnt(14)
	v_add_u32_e32 v17, v0, v15
	s_waitcnt vmcnt(13)
	v_add_u32_e32 v17, v17, v1
	s_waitcnt vmcnt(12)
	v_add_u32_e32 v17, v17, v2
	s_waitcnt vmcnt(11)
	v_add_u32_e32 v17, v17, v3
	s_waitcnt vmcnt(10)
	v_add_u32_e32 v17, v17, v4
	s_waitcnt vmcnt(9)
	v_add_u32_e32 v17, v17, v5
	s_waitcnt vmcnt(8)
	v_add_u32_e32 v17, v17, v6
	s_waitcnt vmcnt(7)
	v_add_u32_e32 v17, v17, v7
	s_waitcnt vmcnt(6)
	v_add_u32_e32 v17, v17, v8
	s_waitcnt vmcnt(5)
	v_add_u32_e32 v17, v17, v9
	s_waitcnt vmcnt(4)
	v_add_u32_e32 v17, v17, v10
	s_waitcnt vmcnt(3)
	v_add_u32_e32 v17, v17, v11
	s_waitcnt vmcnt(2)
	v_add_u32_e32 v17, v17, v12
	s_waitcnt vmcnt(1)
	v_add_u32_e32 v17, v17, v13
	s_waitcnt vmcnt(0)
	v_add_u32_e32 v17, v17, v14
	v_cmp_eq_u32_e32 vcc, s14, v17
	s_cbranch_vccnz .LBB0_201
	s_and_b32 s15, s3, 0xff
	s_cmp_eq_u32 s15, 0
	s_mov_b64 s[88:89], -1
	s_nop 0
	s_cbranch_scc0 .LBB0_206
	global_load_dword v17, v16, s[6:7] sc1
	s_waitcnt vmcnt(0)
	v_cmp_eq_u32_e32 vcc, 0, v17
	s_cbranch_vccnz .LBB0_208
	s_mov_b64 s[88:89], 0

; __device__ __forceinline__ unsigned xb_ld(unsigned* p)              { return __hip_atomic_load(p, __ATOMIC_RELAXED, __HIP_MEMORY_SCOPE_AGENT); }
; #define XB_SPIN(cond, bar) do { unsigned _sp = 0; while (cond) { __builtin_amdgcn_s_sleep(1); \
;     if ((++_sp & 255u) == 0u) { if (xb_ld(&(bar)[XB_TMO])) break; if (_sp > XB_SPIN_CAP) { atomicAdd(&(bar)[XB_TMO], 1u); break; } } } } while (0)
; __device__ __forceinline__ void xcd_barrier(const XcdBarrier& b) {
;     ...
;             else XB_SPIN(xb_ld(&bar[XB_TOPGEN]) == tg, bar);
.LBB0_220:
	s_and_b32 s14, s3, 0xff
	s_mov_b64 s[40:41], -1
	s_cmp_lg_u32 s14, 0
	s_mov_b64 s[48:49], -1
	s_nop 0
	s_cbranch_scc1 .LBB0_223
	global_load_dword v2, v0, s[16:17] sc1
	s_waitcnt vmcnt(0)
	v_cmp_eq_u32_e32 vcc, 0, v2
	s_cbranch_vccnz .LBB0_225
	s_mov_b64 s[48:49], 0
	s_mov_b64 s[44:45], -1

; __device__ __forceinline__ unsigned xb_ld(unsigned* p)              { return __hip_atomic_load(p, __ATOMIC_RELAXED, __HIP_MEMORY_SCOPE_AGENT); }
; #define XB_SPIN(cond, bar) do { unsigned _sp = 0; while (cond) { __builtin_amdgcn_s_sleep(1); \
;     if ((++_sp & 255u) == 0u) { if (xb_ld(&(bar)[XB_TMO])) break; if (_sp > XB_SPIN_CAP) { atomicAdd(&(bar)[XB_TMO], 1u); break; } } } } while (0)
; __device__ __forceinline__ void xcd_barrier(const XcdBarrier& b) {
;     ...
;             XB_SPIN(xb_ld(&bar[XB_XGEN(b.x)]) == gen, bar);
.LBB0_237:
	s_and_b32 s14, s3, 0xff
	s_cmp_lg_u32 s14, 0
	s_mov_b64 s[44:45], -1
	s_nop 0
	s_cbranch_scc1 .LBB0_240
	global_load_dword v1, v0, s[16:17] sc1
	s_waitcnt vmcnt(0)
	v_cmp_eq_u32_e32 vcc, 0, v1
	s_cbranch_vccnz .LBB0_242
	s_mov_b64 s[44:45], 0
	s_mov_b64 s[40:41], -1

; __device__ __forceinline__ unsigned xb_ld(unsigned* p)              { return __hip_atomic_load(p, __ATOMIC_RELAXED, __HIP_MEMORY_SCOPE_AGENT); }
; __device__ __forceinline__ void xcd_barrier_complete(unsigned* bar, unsigned x, unsigned& nloc, unsigned& nx) {
;     ...
;     for (;;) {
;         sum = 0u; cnt = 0u; mine = 0u;
; #pragma unroll
;         for (unsigned j = 0; j < 16; ++j) { const unsigned c = xb_ld(&bar[XB_XCNT(j)]); sum += c; cnt += (c > 0u) ? 1u : 0u; mine = (j == x) ? c : mine; }
;         if (sum == G) break;
;         __builtin_amdgcn_s_sleep(1);
;         if ((++sp & 255u) == 0u) { if (xb_ld(&bar[XB_TMO])) break; if (sp > XB_SPIN_CAP) { atomicAdd(&bar[XB_TMO], 1u); break; } }
;     }
.LBB0_360:
	global_load_dword v15, v16, s[8:9] sc1
	global_load_dword v0, v16, s[10:11] sc1
	global_load_dword v1, v16, s[26:27] sc1
	global_load_dword v2, v16, s[28:29] sc1
	global_load_dword v3, v16, s[40:41] sc1
	global_load_dword v4, v16, s[44:45] sc1
	global_load_dword v5, v16, s[48:49] sc1
	global_load_dword v6, v16, s[50:51] sc1
	global_load_dword v7, v16, s[52:53] sc1
	global_load_dword v8, v16, s[54:55] sc1
	global_load_dword v9, v16, s[56:57] sc1
	global_load_dword v10, v16, s[58:59] sc1
	global_load_dword v11, v16, s[60:61] sc1
	global_load_dword v12, v16, s[62:63] sc1
	global_load_dword v13, v16, s[64:65] sc1
	global_load_dword v14, v16, s[66:67] sc1
	s_mov_b64 s[86:87], -1
	s_mov_b64 s[88:89], -1
	s_waitcnt vmcnt(14)
	v_add_u32_e32 v17, v0, v15
	s_waitcnt vmcnt(13)
	v_add_u32_e32 v17, v17, v1
	s_waitcnt vmcnt(12)
	v_add_u32_e32 v17, v17, v2
	s_waitcnt vmcnt(11)
	v_add_u32_e32 v17, v17, v3
	s_waitcnt vmcnt(10)
	v_add_u32_e32 v17, v17, v4
	s_waitcnt vmcnt(9)
	v_add_u32_e32 v17, v17, v5
	s_waitcnt vmcnt(8)
	v_add_u32_e32 v17, v17, v6
	s_waitcnt vmcnt(7)
	v_add_u32_e32 v17, v17, v7
	s_waitcnt vmcnt(6)
	v_add_u32_e32 v17, v17, v8
	s_waitcnt vmcnt(5)
	v_add_u32_e32 v17, v17, v9
	s_waitcnt vmcnt(4)
	v_add_u32_e32 v17, v17, v10
	s_waitcnt vmcnt(3)
	v_add_u32_e32 v17, v17, v11
	s_waitcnt vmcnt(2)
	v_add_u32_e32 v17, v17, v12
	s_waitcnt vmcnt(1)
	v_add_u32_e32 v17, v17, v13
	s_waitcnt vmcnt(0)
	v_add_u32_e32 v17, v17, v14
	v_cmp_eq_u32_e32 vcc, s14, v17
	s_cbranch_vccnz .LBB0_359
	s_and_b32 s15, s3, 0xff
	s_cmp_eq_u32 s15, 0
	s_mov_b64 s[90:91], -1
	s_nop 0
	s_cbranch_scc0 .LBB0_364
	global_load_dword v17, v16, s[6:7] sc1
	s_waitcnt vmcnt(0)
	v_cmp_eq_u32_e32 vcc, 0, v17
	s_cbranch_vccnz .LBB0_366
	s_mov_b64 s[90:91], 0

; __device__ __forceinline__ unsigned xb_ld(unsigned* p)              { return __hip_atomic_load(p, __ATOMIC_RELAXED, __HIP_MEMORY_SCOPE_AGENT); }
; #define XB_SPIN(cond, bar) do { unsigned _sp = 0; while (cond) { __builtin_amdgcn_s_sleep(1); \
;     if ((++_sp & 255u) == 0u) { if (xb_ld(&(bar)[XB_TMO])) break; if (_sp > XB_SPIN_CAP) { atomicAdd(&(bar)[XB_TMO], 1u); break; } } } } while (0)
; __device__ __forceinline__ void xcd_barrier(const XcdBarrier& b) {
;     ...
;             else XB_SPIN(xb_ld(&bar[XB_TOPGEN]) == tg, bar);
.LBB0_378:
	s_and_b32 s14, s3, 0xff
	s_mov_b64 s[48:49], -1
	s_cmp_lg_u32 s14, 0
	s_mov_b64 s[52:53], -1
	s_nop 0
	s_cbranch_scc1 .LBB0_381
	global_load_dword v2, v0, s[26:27] sc1
	s_waitcnt vmcnt(0)
	v_cmp_eq_u32_e32 vcc, 0, v2
	s_cbranch_vccnz .LBB0_383
	s_mov_b64 s[52:53], 0
	s_mov_b64 s[50:51], -1

; __device__ __forceinline__ unsigned xb_ld(unsigned* p)              { return __hip_atomic_load(p, __ATOMIC_RELAXED, __HIP_MEMORY_SCOPE_AGENT); }
; #define XB_SPIN(cond, bar) do { unsigned _sp = 0; while (cond) { __builtin_amdgcn_s_sleep(1); \
;     if ((++_sp & 255u) == 0u) { if (xb_ld(&(bar)[XB_TMO])) break; if (_sp > XB_SPIN_CAP) { atomicAdd(&(bar)[XB_TMO], 1u); break; } } } } while (0)
; __device__ __forceinline__ void xcd_barrier(const XcdBarrier& b) {
;     ...
;             XB_SPIN(xb_ld(&bar[XB_XGEN(b.x)]) == gen, bar);
.LBB0_395:
	s_and_b32 s14, s3, 0xff
	s_cmp_lg_u32 s14, 0
	s_mov_b64 s[50:51], -1
	s_nop 0
	s_cbranch_scc1 .LBB0_398
	global_load_dword v1, v0, s[26:27] sc1
	s_waitcnt vmcnt(0)
	v_cmp_eq_u32_e32 vcc, 0, v1
	s_cbranch_vccnz .LBB0_400
	s_mov_b64 s[50:51], 0
	s_mov_b64 s[48:49], -1

; __device__ __forceinline__ unsigned xb_ld(unsigned* p)              { return __hip_atomic_load(p, __ATOMIC_RELAXED, __HIP_MEMORY_SCOPE_AGENT); }
; __device__ __forceinline__ void xcd_barrier_complete(unsigned* bar, unsigned x, unsigned& nloc, unsigned& nx) {
;     ...
;     for (;;) {
;         sum = 0u; cnt = 0u; mine = 0u;
; #pragma unroll
;         for (unsigned j = 0; j < 16; ++j) { const unsigned c = xb_ld(&bar[XB_XCNT(j)]); sum += c; cnt += (c > 0u) ? 1u : 0u; mine = (j == x) ? c : mine; }
;         if (sum == G) break;
;         __builtin_amdgcn_s_sleep(1);
;         if ((++sp & 255u) == 0u) { if (xb_ld(&bar[XB_TMO])) break; if (sp > XB_SPIN_CAP) { atomicAdd(&bar[XB_TMO], 1u); break; } }
;     }
.LBB0_516:
	global_load_dword v15, v16, s[8:9] sc1
	global_load_dword v0, v16, s[10:11] sc1
	global_load_dword v1, v16, s[40:41] sc1
	global_load_dword v2, v16, s[44:45] sc1
	global_load_dword v3, v16, s[48:49] sc1
	global_load_dword v4, v16, s[50:51] sc1
	global_load_dword v5, v16, s[52:53] sc1
	global_load_dword v6, v16, s[54:55] sc1
	global_load_dword v7, v16, s[56:57] sc1
	global_load_dword v8, v16, s[58:59] sc1
	global_load_dword v9, v16, s[60:61] sc1
	global_load_dword v10, v16, s[62:63] sc1
	global_load_dword v11, v16, s[64:65] sc1
	global_load_dword v12, v16, s[66:67] sc1
	global_load_dword v13, v16, s[84:85] sc1
	global_load_dword v14, v16, s[86:87] sc1
	s_mov_b64 s[88:89], -1
	s_mov_b64 s[90:91], -1
	s_waitcnt vmcnt(14)
	v_add_u32_e32 v17, v0, v15
	s_waitcnt vmcnt(13)
	v_add_u32_e32 v17, v17, v1
	s_waitcnt vmcnt(12)
	v_add_u32_e32 v17, v17, v2
	s_waitcnt vmcnt(11)
	v_add_u32_e32 v17, v17, v3
	s_waitcnt vmcnt(10)
	v_add_u32_e32 v17, v17, v4
	s_waitcnt vmcnt(9)
	v_add_u32_e32 v17, v17, v5
	s_waitcnt vmcnt(8)
	v_add_u32_e32 v17, v17, v6
	s_waitcnt vmcnt(7)
	v_add_u32_e32 v17, v17, v7
	s_waitcnt vmcnt(6)
	v_add_u32_e32 v17, v17, v8
	s_waitcnt vmcnt(5)
	v_add_u32_e32 v17, v17, v9
	s_waitcnt vmcnt(4)
	v_add_u32_e32 v17, v17, v10
	s_waitcnt vmcnt(3)
	v_add_u32_e32 v17, v17, v11
	s_waitcnt vmcnt(2)
	v_add_u32_e32 v17, v17, v12
	s_waitcnt vmcnt(1)
	v_add_u32_e32 v17, v17, v13
	s_waitcnt vmcnt(0)
	v_add_u32_e32 v17, v17, v14
	v_cmp_eq_u32_e32 vcc, s14, v17
	s_cbranch_vccnz .LBB0_515
	s_and_b32 s15, s3, 0xff
	s_cmp_eq_u32 s15, 0
	s_mov_b64 s[92:93], -1
	s_nop 0
	s_cbranch_scc0 .LBB0_520
	global_load_dword v17, v16, s[6:7] sc1
	s_waitcnt vmcnt(0)
	v_cmp_eq_u32_e32 vcc, 0, v17
	s_cbranch_vccnz .LBB0_522
	s_mov_b64 s[92:93], 0

; __device__ __forceinline__ unsigned xb_ld(unsigned* p)              { return __hip_atomic_load(p, __ATOMIC_RELAXED, __HIP_MEMORY_SCOPE_AGENT); }
; #define XB_SPIN(cond, bar) do { unsigned _sp = 0; while (cond) { __builtin_amdgcn_s_sleep(1); \
;     if ((++_sp & 255u) == 0u) { if (xb_ld(&(bar)[XB_TMO])) break; if (_sp > XB_SPIN_CAP) { atomicAdd(&(bar)[XB_TMO], 1u); break; } } } } while (0)
; __device__ __forceinline__ void xcd_barrier(const XcdBarrier& b) {
;     ...
;             else XB_SPIN(xb_ld(&bar[XB_TOPGEN]) == tg, bar);
.LBB0_534:
	s_and_b32 s14, s3, 0xff
	s_mov_b64 s[52:53], -1
	s_cmp_lg_u32 s14, 0
	s_mov_b64 s[56:57], -1
	s_nop 0
	s_cbranch_scc1 .LBB0_537
	global_load_dword v2, v0, s[40:41] sc1
	s_waitcnt vmcnt(0)
	v_cmp_eq_u32_e32 vcc, 0, v2
	s_cbranch_vccnz .LBB0_539
	s_mov_b64 s[56:57], 0
	s_mov_b64 s[54:55], -1

; __device__ __forceinline__ unsigned xb_ld(unsigned* p)              { return __hip_atomic_load(p, __ATOMIC_RELAXED, __HIP_MEMORY_SCOPE_AGENT); }
; #define XB_SPIN(cond, bar) do { unsigned _sp = 0; while (cond) { __builtin_amdgcn_s_sleep(1); \
;     if ((++_sp & 255u) == 0u) { if (xb_ld(&(bar)[XB_TMO])) break; if (_sp > XB_SPIN_CAP) { atomicAdd(&(bar)[XB_TMO], 1u); break; } } } } while (0)
; __device__ __forceinline__ void xcd_barrier(const XcdBarrier& b) {
;     ...
;             XB_SPIN(xb_ld(&bar[XB_XGEN(b.x)]) == gen, bar);
.LBB0_551:
	s_and_b32 s14, s3, 0xff
	s_cmp_lg_u32 s14, 0
	s_mov_b64 s[54:55], -1
	s_nop 0
	s_cbranch_scc1 .LBB0_554
	global_load_dword v1, v0, s[40:41] sc1
	s_waitcnt vmcnt(0)
	v_cmp_eq_u32_e32 vcc, 0, v1
	s_cbranch_vccnz .LBB0_556
	s_mov_b64 s[54:55], 0
	s_mov_b64 s[52:53], -1

; __device__ __forceinline__ unsigned xb_ld(unsigned* p)              { return __hip_atomic_load(p, __ATOMIC_RELAXED, __HIP_MEMORY_SCOPE_AGENT); }
; __device__ __forceinline__ void xcd_barrier_complete(unsigned* bar, unsigned x, unsigned& nloc, unsigned& nx) {
;     ...
;     for (;;) {
;         sum = 0u; cnt = 0u; mine = 0u;
; #pragma unroll
;         for (unsigned j = 0; j < 16; ++j) { const unsigned c = xb_ld(&bar[XB_XCNT(j)]); sum += c; cnt += (c > 0u) ? 1u : 0u; mine = (j == x) ? c : mine; }
;         if (sum == G) break;
;         __builtin_amdgcn_s_sleep(1);
;         if ((++sp & 255u) == 0u) { if (xb_ld(&bar[XB_TMO])) break; if (sp > XB_SPIN_CAP) { atomicAdd(&bar[XB_TMO], 1u); break; } }
;     }
.LBB0_587:
	global_load_dword v15, v16, s[10:11] sc1
	global_load_dword v0, v16, s[36:37] sc1
	global_load_dword v1, v16, s[38:39] sc1
	global_load_dword v2, v16, s[44:45] sc1
	global_load_dword v3, v16, s[48:49] sc1
	global_load_dword v4, v16, s[50:51] sc1
	global_load_dword v5, v16, s[52:53] sc1
	global_load_dword v6, v16, s[54:55] sc1
	global_load_dword v7, v16, s[56:57] sc1
	global_load_dword v8, v16, s[58:59] sc1
	global_load_dword v9, v16, s[60:61] sc1
	global_load_dword v10, v16, s[62:63] sc1
	global_load_dword v11, v16, s[64:65] sc1
	global_load_dword v12, v16, s[66:67] sc1
	global_load_dword v13, v16, s[84:85] sc1
	global_load_dword v14, v16, s[86:87] sc1
	s_mov_b64 s[88:89], -1
	s_mov_b64 s[90:91], -1
	s_waitcnt vmcnt(14)
	v_add_u32_e32 v17, v0, v15
	s_waitcnt vmcnt(13)
	v_add_u32_e32 v17, v17, v1
	s_waitcnt vmcnt(12)
	v_add_u32_e32 v17, v17, v2
	s_waitcnt vmcnt(11)
	v_add_u32_e32 v17, v17, v3
	s_waitcnt vmcnt(10)
	v_add_u32_e32 v17, v17, v4
	s_waitcnt vmcnt(9)
	v_add_u32_e32 v17, v17, v5
	s_waitcnt vmcnt(8)
	v_add_u32_e32 v17, v17, v6
	s_waitcnt vmcnt(7)
	v_add_u32_e32 v17, v17, v7
	s_waitcnt vmcnt(6)
	v_add_u32_e32 v17, v17, v8
	s_waitcnt vmcnt(5)
	v_add_u32_e32 v17, v17, v9
	s_waitcnt vmcnt(4)
	v_add_u32_e32 v17, v17, v10
	s_waitcnt vmcnt(3)
	v_add_u32_e32 v17, v17, v11
	s_waitcnt vmcnt(2)
	v_add_u32_e32 v17, v17, v12
	s_waitcnt vmcnt(1)
	v_add_u32_e32 v17, v17, v13
	s_waitcnt vmcnt(0)
	v_add_u32_e32 v17, v17, v14
	v_cmp_eq_u32_e32 vcc, s14, v17
	s_cbranch_vccnz .LBB0_586
	s_and_b32 s15, s3, 0xff
	s_cmp_eq_u32 s15, 0
	s_mov_b64 s[92:93], -1
	s_nop 0
	s_cbranch_scc0 .LBB0_591
	global_load_dword v17, v16, s[8:9] sc1
	s_waitcnt vmcnt(0)
	v_cmp_eq_u32_e32 vcc, 0, v17
	s_cbranch_vccnz .LBB0_593
	s_mov_b64 s[92:93], 0

; __device__ __forceinline__ unsigned xb_ld(unsigned* p)              { return __hip_atomic_load(p, __ATOMIC_RELAXED, __HIP_MEMORY_SCOPE_AGENT); }
; #define XB_SPIN(cond, bar) do { unsigned _sp = 0; while (cond) { __builtin_amdgcn_s_sleep(1); \
;     if ((++_sp & 255u) == 0u) { if (xb_ld(&(bar)[XB_TMO])) break; if (_sp > XB_SPIN_CAP) { atomicAdd(&(bar)[XB_TMO], 1u); break; } } } } while (0)
; __device__ __forceinline__ void xcd_barrier(const XcdBarrier& b) {
;     ...
;             else XB_SPIN(xb_ld(&bar[XB_TOPGEN]) == tg, bar);
.LBB0_605:
	s_and_b32 s14, s3, 0xff
	s_mov_b64 s[52:53], -1
	s_cmp_lg_u32 s14, 0
	s_mov_b64 s[56:57], -1
	s_nop 0
	s_cbranch_scc1 .LBB0_608
	global_load_dword v2, v0, s[38:39] sc1
	s_waitcnt vmcnt(0)
	v_cmp_eq_u32_e32 vcc, 0, v2
	s_cbranch_vccnz .LBB0_610
	s_mov_b64 s[56:57], 0
	s_mov_b64 s[54:55], -1

; __device__ __forceinline__ unsigned xb_ld(unsigned* p)              { return __hip_atomic_load(p, __ATOMIC_RELAXED, __HIP_MEMORY_SCOPE_AGENT); }
; #define XB_SPIN(cond, bar) do { unsigned _sp = 0; while (cond) { __builtin_amdgcn_s_sleep(1); \
;     if ((++_sp & 255u) == 0u) { if (xb_ld(&(bar)[XB_TMO])) break; if (_sp > XB_SPIN_CAP) { atomicAdd(&(bar)[XB_TMO], 1u); break; } } } } while (0)
; __device__ __forceinline__ void xcd_barrier(const XcdBarrier& b) {
;     ...
;             XB_SPIN(xb_ld(&bar[XB_XGEN(b.x)]) == gen, bar);
.LBB0_622:
	s_and_b32 s14, s3, 0xff
	s_cmp_lg_u32 s14, 0
	s_mov_b64 s[54:55], -1
	s_nop 0
	s_cbranch_scc1 .LBB0_625
	global_load_dword v1, v0, s[38:39] sc1
	s_waitcnt vmcnt(0)
	v_cmp_eq_u32_e32 vcc, 0, v1
	s_cbranch_vccnz .LBB0_627
	s_mov_b64 s[54:55], 0
	s_mov_b64 s[52:53], -1

; __device__ __forceinline__ unsigned xb_ld(unsigned* p)              { return __hip_atomic_load(p, __ATOMIC_RELAXED, __HIP_MEMORY_SCOPE_AGENT); }
; __device__ __forceinline__ void xcd_barrier_complete(unsigned* bar, unsigned x, unsigned& nloc, unsigned& nx) {
;     ...
;     for (;;) {
;         sum = 0u; cnt = 0u; mine = 0u;
; #pragma unroll
;         for (unsigned j = 0; j < 16; ++j) { const unsigned c = xb_ld(&bar[XB_XCNT(j)]); sum += c; cnt += (c > 0u) ? 1u : 0u; mine = (j == x) ? c : mine; }
;         if (sum == G) break;
;         __builtin_amdgcn_s_sleep(1);
;         if ((++sp & 255u) == 0u) { if (xb_ld(&bar[XB_TMO])) break; if (sp > XB_SPIN_CAP) { atomicAdd(&bar[XB_TMO], 1u); break; } }
;     }
.LBB0_677:
	global_load_dword v15, v16, s[36:37] sc1
	global_load_dword v0, v16, s[38:39] sc1
	global_load_dword v1, v16, s[44:45] sc1
	global_load_dword v2, v16, s[48:49] sc1
	global_load_dword v3, v16, s[50:51] sc1
	global_load_dword v4, v16, s[52:53] sc1
	global_load_dword v5, v16, s[54:55] sc1
	global_load_dword v6, v16, s[56:57] sc1
	global_load_dword v7, v16, s[58:59] sc1
	global_load_dword v8, v16, s[60:61] sc1
	global_load_dword v9, v16, s[62:63] sc1
	global_load_dword v10, v16, s[64:65] sc1
	global_load_dword v11, v16, s[66:67] sc1
	global_load_dword v12, v16, s[82:83] sc1
	global_load_dword v13, v16, s[84:85] sc1
	global_load_dword v14, v16, s[86:87] sc1
	s_mov_b64 s[88:89], -1
	s_mov_b64 s[90:91], -1
	s_waitcnt vmcnt(14)
	v_add_u32_e32 v17, v0, v15
	s_waitcnt vmcnt(13)
	v_add_u32_e32 v17, v17, v1
	s_waitcnt vmcnt(12)
	v_add_u32_e32 v17, v17, v2
	s_waitcnt vmcnt(11)
	v_add_u32_e32 v17, v17, v3
	s_waitcnt vmcnt(10)
	v_add_u32_e32 v17, v17, v4
	s_waitcnt vmcnt(9)
	v_add_u32_e32 v17, v17, v5
	s_waitcnt vmcnt(8)
	v_add_u32_e32 v17, v17, v6
	s_waitcnt vmcnt(7)
	v_add_u32_e32 v17, v17, v7
	s_waitcnt vmcnt(6)
	v_add_u32_e32 v17, v17, v8
	s_waitcnt vmcnt(5)
	v_add_u32_e32 v17, v17, v9
	s_waitcnt vmcnt(4)
	v_add_u32_e32 v17, v17, v10
	s_waitcnt vmcnt(3)
	v_add_u32_e32 v17, v17, v11
	s_waitcnt vmcnt(2)
	v_add_u32_e32 v17, v17, v12
	s_waitcnt vmcnt(1)
	v_add_u32_e32 v17, v17, v13
	s_waitcnt vmcnt(0)
	v_add_u32_e32 v17, v17, v14
	v_cmp_eq_u32_e32 vcc, s14, v17
	s_cbranch_vccnz .LBB0_676
	s_and_b32 s15, s3, 0xff
	s_cmp_eq_u32 s15, 0
	s_mov_b64 s[92:93], -1
	s_nop 0
	s_cbranch_scc0 .LBB0_681
	global_load_dword v17, v16, s[8:9] sc1
	s_waitcnt vmcnt(0)
	v_cmp_eq_u32_e32 vcc, 0, v17
	s_cbranch_vccnz .LBB0_683
	s_mov_b64 s[92:93], 0

; __device__ __forceinline__ unsigned xb_ld(unsigned* p)              { return __hip_atomic_load(p, __ATOMIC_RELAXED, __HIP_MEMORY_SCOPE_AGENT); }
; #define XB_SPIN(cond, bar) do { unsigned _sp = 0; while (cond) { __builtin_amdgcn_s_sleep(1); \
;     if ((++_sp & 255u) == 0u) { if (xb_ld(&(bar)[XB_TMO])) break; if (_sp > XB_SPIN_CAP) { atomicAdd(&(bar)[XB_TMO], 1u); break; } } } } while (0)
; __device__ __forceinline__ void xcd_barrier(const XcdBarrier& b) {
;     ...
;             else XB_SPIN(xb_ld(&bar[XB_TOPGEN]) == tg, bar);
.LBB0_695:
	s_and_b32 s14, s3, 0xff
	s_mov_b64 s[54:55], -1
	s_cmp_lg_u32 s14, 0
	s_mov_b64 s[58:59], -1
	s_nop 0
	s_cbranch_scc1 .LBB0_698
	global_load_dword v2, v0, s[44:45] sc1
	s_waitcnt vmcnt(0)
	v_cmp_eq_u32_e32 vcc, 0, v2
	s_cbranch_vccnz .LBB0_700
	s_mov_b64 s[58:59], 0
	s_mov_b64 s[56:57], -1

; __device__ __forceinline__ unsigned xb_ld(unsigned* p)              { return __hip_atomic_load(p, __ATOMIC_RELAXED, __HIP_MEMORY_SCOPE_AGENT); }
; #define XB_SPIN(cond, bar) do { unsigned _sp = 0; while (cond) { __builtin_amdgcn_s_sleep(1); \
;     if ((++_sp & 255u) == 0u) { if (xb_ld(&(bar)[XB_TMO])) break; if (_sp > XB_SPIN_CAP) { atomicAdd(&(bar)[XB_TMO], 1u); break; } } } } while (0)
; __device__ __forceinline__ void xcd_barrier(const XcdBarrier& b) {
;     ...
;             XB_SPIN(xb_ld(&bar[XB_XGEN(b.x)]) == gen, bar);
.LBB0_712:
	s_and_b32 s14, s3, 0xff
	s_cmp_lg_u32 s14, 0
	s_mov_b64 s[56:57], -1
	s_nop 0
	s_cbranch_scc1 .LBB0_715
	global_load_dword v1, v0, s[44:45] sc1
	s_waitcnt vmcnt(0)
	v_cmp_eq_u32_e32 vcc, 0, v1
	s_cbranch_vccnz .LBB0_717
	s_mov_b64 s[56:57], 0
	s_mov_b64 s[54:55], -1

; __device__ __forceinline__ unsigned xb_ld(unsigned* p)              { return __hip_atomic_load(p, __ATOMIC_RELAXED, __HIP_MEMORY_SCOPE_AGENT); }
; __device__ __forceinline__ void xcd_barrier_complete(unsigned* bar, unsigned x, unsigned& nloc, unsigned& nx) {
;     ...
;     for (;;) {
;         sum = 0u; cnt = 0u; mine = 0u;
; #pragma unroll
;         for (unsigned j = 0; j < 16; ++j) { const unsigned c = xb_ld(&bar[XB_XCNT(j)]); sum += c; cnt += (c > 0u) ? 1u : 0u; mine = (j == x) ? c : mine; }
;         if (sum == G) break;
;         __builtin_amdgcn_s_sleep(1);
;         if ((++sp & 255u) == 0u) { if (xb_ld(&bar[XB_TMO])) break; if (sp > XB_SPIN_CAP) { atomicAdd(&bar[XB_TMO], 1u); break; } }
;     }
.LBB0_749:
	global_load_dword v15, v16, s[10:11] sc1
	global_load_dword v0, v16, s[36:37] sc1
	global_load_dword v1, v16, s[38:39] sc1
	global_load_dword v2, v16, s[44:45] sc1
	global_load_dword v3, v16, s[48:49] sc1
	global_load_dword v4, v16, s[50:51] sc1
	global_load_dword v5, v16, s[52:53] sc1
	global_load_dword v6, v16, s[54:55] sc1
	global_load_dword v7, v16, s[56:57] sc1
	global_load_dword v8, v16, s[58:59] sc1
	global_load_dword v9, v16, s[60:61] sc1
	global_load_dword v10, v16, s[62:63] sc1
	global_load_dword v11, v16, s[64:65] sc1
	global_load_dword v12, v16, s[66:67] sc1
	global_load_dword v13, v16, s[82:83] sc1
	global_load_dword v14, v16, s[84:85] sc1
	s_mov_b64 s[86:87], -1
	s_mov_b64 s[88:89], -1
	s_waitcnt vmcnt(14)
	v_add_u32_e32 v17, v0, v15
	s_waitcnt vmcnt(13)
	v_add_u32_e32 v17, v17, v1
	s_waitcnt vmcnt(12)
	v_add_u32_e32 v17, v17, v2
	s_waitcnt vmcnt(11)
	v_add_u32_e32 v17, v17, v3
	s_waitcnt vmcnt(10)
	v_add_u32_e32 v17, v17, v4
	s_waitcnt vmcnt(9)
	v_add_u32_e32 v17, v17, v5
	s_waitcnt vmcnt(8)
	v_add_u32_e32 v17, v17, v6
	s_waitcnt vmcnt(7)
	v_add_u32_e32 v17, v17, v7
	s_waitcnt vmcnt(6)
	v_add_u32_e32 v17, v17, v8
	s_waitcnt vmcnt(5)
	v_add_u32_e32 v17, v17, v9
	s_waitcnt vmcnt(4)
	v_add_u32_e32 v17, v17, v10
	s_waitcnt vmcnt(3)
	v_add_u32_e32 v17, v17, v11
	s_waitcnt vmcnt(2)
	v_add_u32_e32 v17, v17, v12
	s_waitcnt vmcnt(1)
	v_add_u32_e32 v17, v17, v13
	s_waitcnt vmcnt(0)
	v_add_u32_e32 v17, v17, v14
	v_cmp_eq_u32_e32 vcc, s14, v17
	s_cbranch_vccnz .LBB0_748
	s_and_b32 s15, s3, 0xff
	s_cmp_eq_u32 s15, 0
	s_mov_b64 s[90:91], -1
	s_nop 0
	s_cbranch_scc0 .LBB0_753
	global_load_dword v17, v16, s[8:9] sc1
	s_waitcnt vmcnt(0)
	v_cmp_eq_u32_e32 vcc, 0, v17
	s_cbranch_vccnz .LBB0_755
	s_mov_b64 s[90:91], 0

; __device__ __forceinline__ unsigned xb_ld(unsigned* p)              { return __hip_atomic_load(p, __ATOMIC_RELAXED, __HIP_MEMORY_SCOPE_AGENT); }
; __device__ __forceinline__ void xcd_barrier_complete(unsigned* bar, unsigned x, unsigned& nloc, unsigned& nx) {
;     ...
;     for (;;) {
;         sum = 0u; cnt = 0u; mine = 0u;
; #pragma unroll
;         for (unsigned j = 0; j < 16; ++j) { const unsigned c = xb_ld(&bar[XB_XCNT(j)]); sum += c; cnt += (c > 0u) ? 1u : 0u; mine = (j == x) ? c : mine; }
;         if (sum == G) break;
;         __builtin_amdgcn_s_sleep(1);
;         if ((++sp & 255u) == 0u) { if (xb_ld(&bar[XB_TMO])) break; if (sp > XB_SPIN_CAP) { atomicAdd(&bar[XB_TMO], 1u); break; } }
;     }
.LBB0_810:
	global_load_dword v15, v16, s[10:11] sc1
	global_load_dword v0, v16, s[36:37] sc1
	global_load_dword v1, v16, s[38:39] sc1
	global_load_dword v2, v16, s[42:43] sc1
	global_load_dword v3, v16, s[44:45] sc1
	global_load_dword v4, v16, s[48:49] sc1
	global_load_dword v5, v16, s[50:51] sc1
	global_load_dword v6, v16, s[52:53] sc1
	global_load_dword v7, v16, s[54:55] sc1
	global_load_dword v8, v16, s[56:57] sc1
	global_load_dword v9, v16, s[58:59] sc1
	global_load_dword v10, v16, s[60:61] sc1
	global_load_dword v11, v16, s[62:63] sc1
	global_load_dword v12, v16, s[64:65] sc1
	global_load_dword v13, v16, s[66:67] sc1
	global_load_dword v14, v16, s[82:83] sc1
	s_mov_b64 s[84:85], -1
	s_mov_b64 s[86:87], -1
	s_waitcnt vmcnt(14)
	v_add_u32_e32 v17, v0, v15
	s_waitcnt vmcnt(13)
	v_add_u32_e32 v17, v17, v1
	s_waitcnt vmcnt(12)
	v_add_u32_e32 v17, v17, v2
	s_waitcnt vmcnt(11)
	v_add_u32_e32 v17, v17, v3
	s_waitcnt vmcnt(10)
	v_add_u32_e32 v17, v17, v4
	s_waitcnt vmcnt(9)
	v_add_u32_e32 v17, v17, v5
	s_waitcnt vmcnt(8)
	v_add_u32_e32 v17, v17, v6
	s_waitcnt vmcnt(7)
	v_add_u32_e32 v17, v17, v7
	s_waitcnt vmcnt(6)
	v_add_u32_e32 v17, v17, v8
	s_waitcnt vmcnt(5)
	v_add_u32_e32 v17, v17, v9
	s_waitcnt vmcnt(4)
	v_add_u32_e32 v17, v17, v10
	s_waitcnt vmcnt(3)
	v_add_u32_e32 v17, v17, v11
	s_waitcnt vmcnt(2)
	v_add_u32_e32 v17, v17, v12
	s_waitcnt vmcnt(1)
	v_add_u32_e32 v17, v17, v13
	s_waitcnt vmcnt(0)
	v_add_u32_e32 v17, v17, v14
	v_cmp_eq_u32_e32 vcc, s14, v17
	s_cbranch_vccnz .LBB0_809
	s_and_b32 s15, s3, 0xff
	s_cmp_eq_u32 s15, 0
	s_mov_b64 s[88:89], -1
	s_nop 0
	s_cbranch_scc0 .LBB0_814
	global_load_dword v17, v16, s[8:9] sc1
	s_waitcnt vmcnt(0)
	v_cmp_eq_u32_e32 vcc, 0, v17
	s_cbranch_vccnz .LBB0_816
	s_mov_b64 s[88:89], 0

; __device__ __forceinline__ unsigned xb_ld(unsigned* p)              { return __hip_atomic_load(p, __ATOMIC_RELAXED, __HIP_MEMORY_SCOPE_AGENT); }
; #define XB_SPIN(cond, bar) do { unsigned _sp = 0; while (cond) { __builtin_amdgcn_s_sleep(1); \
;     if ((++_sp & 255u) == 0u) { if (xb_ld(&(bar)[XB_TMO])) break; if (_sp > XB_SPIN_CAP) { atomicAdd(&(bar)[XB_TMO], 1u); break; } } } } while (0)
; __device__ __forceinline__ void xcd_barrier(const XcdBarrier& b) {
;     ...
;             else XB_SPIN(xb_ld(&bar[XB_TOPGEN]) == tg, bar);
.LBB0_828:
	s_and_b32 s14, s3, 0xff
	s_mov_b64 s[50:51], -1
	s_cmp_lg_u32 s14, 0
	s_mov_b64 s[54:55], -1
	s_nop 0
	s_cbranch_scc1 .LBB0_831
	global_load_dword v2, v0, s[38:39] sc1
	s_waitcnt vmcnt(0)
	v_cmp_eq_u32_e32 vcc, 0, v2
	s_cbranch_vccnz .LBB0_833
	s_mov_b64 s[54:55], 0
	s_mov_b64 s[52:53], -1

; __device__ __forceinline__ unsigned xb_ld(unsigned* p)              { return __hip_atomic_load(p, __ATOMIC_RELAXED, __HIP_MEMORY_SCOPE_AGENT); }
; #define XB_SPIN(cond, bar) do { unsigned _sp = 0; while (cond) { __builtin_amdgcn_s_sleep(1); \
;     if ((++_sp & 255u) == 0u) { if (xb_ld(&(bar)[XB_TMO])) break; if (_sp > XB_SPIN_CAP) { atomicAdd(&(bar)[XB_TMO], 1u); break; } } } } while (0)
; __device__ __forceinline__ void xcd_barrier(const XcdBarrier& b) {
;     ...
;             XB_SPIN(xb_ld(&bar[XB_XGEN(b.x)]) == gen, bar);
.LBB0_845:
	s_and_b32 s14, s3, 0xff
	s_cmp_lg_u32 s14, 0
	s_mov_b64 s[52:53], -1
	s_nop 0
	s_cbranch_scc1 .LBB0_848
	global_load_dword v1, v0, s[38:39] sc1
	s_waitcnt vmcnt(0)
	v_cmp_eq_u32_e32 vcc, 0, v1
	s_cbranch_vccnz .LBB0_850
	s_mov_b64 s[52:53], 0
	s_mov_b64 s[50:51], -1

; __device__ __forceinline__ unsigned xb_ld(unsigned* p)              { return __hip_atomic_load(p, __ATOMIC_RELAXED, __HIP_MEMORY_SCOPE_AGENT); }
; __device__ __forceinline__ void xcd_barrier_complete(unsigned* bar, unsigned x, unsigned& nloc, unsigned& nx) {
;     ...
;     for (;;) {
;         sum = 0u; cnt = 0u; mine = 0u;
; #pragma unroll
;         for (unsigned j = 0; j < 16; ++j) { const unsigned c = xb_ld(&bar[XB_XCNT(j)]); sum += c; cnt += (c > 0u) ? 1u : 0u; mine = (j == x) ? c : mine; }
;         if (sum == G) break;
;         __builtin_amdgcn_s_sleep(1);
;         if ((++sp & 255u) == 0u) { if (xb_ld(&bar[XB_TMO])) break; if (sp > XB_SPIN_CAP) { atomicAdd(&bar[XB_TMO], 1u); break; } }
;     }
.LBB0_900:
	global_load_dword v15, v16, s[36:37] sc1
	global_load_dword v0, v16, s[38:39] sc1
	global_load_dword v1, v16, s[42:43] sc1
	global_load_dword v2, v16, s[44:45] sc1
	global_load_dword v3, v16, s[48:49] sc1
	global_load_dword v4, v16, s[50:51] sc1
	global_load_dword v5, v16, s[52:53] sc1
	global_load_dword v6, v16, s[54:55] sc1
	global_load_dword v7, v16, s[56:57] sc1
	global_load_dword v8, v16, s[58:59] sc1
	global_load_dword v9, v16, s[60:61] sc1
	global_load_dword v10, v16, s[62:63] sc1
	global_load_dword v11, v16, s[64:65] sc1
	global_load_dword v12, v16, s[66:67] sc1
	global_load_dword v13, v16, s[82:83] sc1
	global_load_dword v14, v16, s[84:85] sc1
	s_mov_b64 s[86:87], -1
	s_mov_b64 s[88:89], -1
	s_waitcnt vmcnt(14)
	v_add_u32_e32 v17, v0, v15
	s_waitcnt vmcnt(13)
	v_add_u32_e32 v17, v17, v1
	s_waitcnt vmcnt(12)
	v_add_u32_e32 v17, v17, v2
	s_waitcnt vmcnt(11)
	v_add_u32_e32 v17, v17, v3
	s_waitcnt vmcnt(10)
	v_add_u32_e32 v17, v17, v4
	s_waitcnt vmcnt(9)
	v_add_u32_e32 v17, v17, v5
	s_waitcnt vmcnt(8)
	v_add_u32_e32 v17, v17, v6
	s_waitcnt vmcnt(7)
	v_add_u32_e32 v17, v17, v7
	s_waitcnt vmcnt(6)
	v_add_u32_e32 v17, v17, v8
	s_waitcnt vmcnt(5)
	v_add_u32_e32 v17, v17, v9
	s_waitcnt vmcnt(4)
	v_add_u32_e32 v17, v17, v10
	s_waitcnt vmcnt(3)
	v_add_u32_e32 v17, v17, v11
	s_waitcnt vmcnt(2)
	v_add_u32_e32 v17, v17, v12
	s_waitcnt vmcnt(1)
	v_add_u32_e32 v17, v17, v13
	s_waitcnt vmcnt(0)
	v_add_u32_e32 v17, v17, v14
	v_cmp_eq_u32_e32 vcc, s14, v17
	s_cbranch_vccnz .LBB0_899
	s_and_b32 s15, s3, 0xff
	s_cmp_eq_u32 s15, 0
	s_mov_b64 s[90:91], -1
	s_nop 0
	s_cbranch_scc0 .LBB0_904
	global_load_dword v17, v16, s[10:11] sc1
	s_waitcnt vmcnt(0)
	v_cmp_eq_u32_e32 vcc, 0, v17
	s_cbranch_vccnz .LBB0_906
	s_mov_b64 s[90:91], 0

; __device__ __forceinline__ unsigned xb_ld(unsigned* p)              { return __hip_atomic_load(p, __ATOMIC_RELAXED, __HIP_MEMORY_SCOPE_AGENT); }
; #define XB_SPIN(cond, bar) do { unsigned _sp = 0; while (cond) { __builtin_amdgcn_s_sleep(1); \
;     if ((++_sp & 255u) == 0u) { if (xb_ld(&(bar)[XB_TMO])) break; if (_sp > XB_SPIN_CAP) { atomicAdd(&(bar)[XB_TMO], 1u); break; } } } } while (0)
; __device__ __forceinline__ void xcd_barrier(const XcdBarrier& b) {
;     ...
;             else XB_SPIN(xb_ld(&bar[XB_TOPGEN]) == tg, bar);
.LBB0_918:
	s_and_b32 s14, s3, 0xff
	s_mov_b64 s[52:53], -1
	s_cmp_lg_u32 s14, 0
	s_mov_b64 s[56:57], -1
	s_nop 0
	s_cbranch_scc1 .LBB0_921
	global_load_dword v2, v0, s[42:43] sc1
	s_waitcnt vmcnt(0)
	v_cmp_eq_u32_e32 vcc, 0, v2
	s_cbranch_vccnz .LBB0_923
	s_mov_b64 s[56:57], 0
	s_mov_b64 s[54:55], -1

; __device__ __forceinline__ unsigned xb_ld(unsigned* p)              { return __hip_atomic_load(p, __ATOMIC_RELAXED, __HIP_MEMORY_SCOPE_AGENT); }
; #define XB_SPIN(cond, bar) do { unsigned _sp = 0; while (cond) { __builtin_amdgcn_s_sleep(1); \
;     if ((++_sp & 255u) == 0u) { if (xb_ld(&(bar)[XB_TMO])) break; if (_sp > XB_SPIN_CAP) { atomicAdd(&(bar)[XB_TMO], 1u); break; } } } } while (0)
; __device__ __forceinline__ void xcd_barrier(const XcdBarrier& b) {
;     ...
;             XB_SPIN(xb_ld(&bar[XB_XGEN(b.x)]) == gen, bar);
.LBB0_935:
	s_and_b32 s14, s3, 0xff
	s_cmp_lg_u32 s14, 0
	s_mov_b64 s[54:55], -1
	s_nop 0
	s_cbranch_scc1 .LBB0_938
	global_load_dword v1, v0, s[42:43] sc1
	s_waitcnt vmcnt(0)
	v_cmp_eq_u32_e32 vcc, 0, v1
	s_cbranch_vccnz .LBB0_940
	s_mov_b64 s[54:55], 0
	s_mov_b64 s[52:53], -1

; __device__ __forceinline__ unsigned xb_ld(unsigned* p)              { return __hip_atomic_load(p, __ATOMIC_RELAXED, __HIP_MEMORY_SCOPE_AGENT); }
; __device__ __forceinline__ void xcd_barrier_complete(unsigned* bar, unsigned x, unsigned& nloc, unsigned& nx) {
;     ...
;     for (;;) {
;         sum = 0u; cnt = 0u; mine = 0u;
; #pragma unroll
;         for (unsigned j = 0; j < 16; ++j) { const unsigned c = xb_ld(&bar[XB_XCNT(j)]); sum += c; cnt += (c > 0u) ? 1u : 0u; mine = (j == x) ? c : mine; }
;         if (sum == G) break;
;         __builtin_amdgcn_s_sleep(1);
;         if ((++sp & 255u) == 0u) { if (xb_ld(&bar[XB_TMO])) break; if (sp > XB_SPIN_CAP) { atomicAdd(&bar[XB_TMO], 1u); break; } }
;     }
.LBB0_968:
	global_load_dword v15, v16, s[12:13] sc1
	global_load_dword v0, v16, s[36:37] sc1
	global_load_dword v1, v16, s[38:39] sc1
	global_load_dword v2, v16, s[42:43] sc1
	global_load_dword v3, v16, s[44:45] sc1
	global_load_dword v4, v16, s[48:49] sc1
	global_load_dword v5, v16, s[50:51] sc1
	global_load_dword v6, v16, s[52:53] sc1
	global_load_dword v7, v16, s[54:55] sc1
	global_load_dword v8, v16, s[56:57] sc1
	global_load_dword v9, v16, s[58:59] sc1
	global_load_dword v10, v16, s[60:61] sc1
	global_load_dword v11, v16, s[62:63] sc1
	global_load_dword v12, v16, s[64:65] sc1
	global_load_dword v13, v16, s[66:67] sc1
	global_load_dword v14, v16, s[82:83] sc1
	s_mov_b64 s[84:85], -1
	s_mov_b64 s[86:87], -1
	s_waitcnt vmcnt(14)
	v_add_u32_e32 v17, v0, v15
	s_waitcnt vmcnt(13)
	v_add_u32_e32 v17, v17, v1
	s_waitcnt vmcnt(12)
	v_add_u32_e32 v17, v17, v2
	s_waitcnt vmcnt(11)
	v_add_u32_e32 v17, v17, v3
	s_waitcnt vmcnt(10)
	v_add_u32_e32 v17, v17, v4
	s_waitcnt vmcnt(9)
	v_add_u32_e32 v17, v17, v5
	s_waitcnt vmcnt(8)
	v_add_u32_e32 v17, v17, v6
	s_waitcnt vmcnt(7)
	v_add_u32_e32 v17, v17, v7
	s_waitcnt vmcnt(6)
	v_add_u32_e32 v17, v17, v8
	s_waitcnt vmcnt(5)
	v_add_u32_e32 v17, v17, v9
	s_waitcnt vmcnt(4)
	v_add_u32_e32 v17, v17, v10
	s_waitcnt vmcnt(3)
	v_add_u32_e32 v17, v17, v11
	s_waitcnt vmcnt(2)
	v_add_u32_e32 v17, v17, v12
	s_waitcnt vmcnt(1)
	v_add_u32_e32 v17, v17, v13
	s_waitcnt vmcnt(0)
	v_add_u32_e32 v17, v17, v14
	v_cmp_eq_u32_e32 vcc, s14, v17
	s_cbranch_vccnz .LBB0_967
	s_and_b32 s15, s3, 0xff
	s_cmp_eq_u32 s15, 0
	s_mov_b64 s[88:89], -1
	s_nop 0
	s_cbranch_scc0 .LBB0_972
	global_load_dword v17, v16, s[10:11] sc1
	s_waitcnt vmcnt(0)
	v_cmp_eq_u32_e32 vcc, 0, v17
	s_cbranch_vccnz .LBB0_974
	s_mov_b64 s[88:89], 0

; __device__ __forceinline__ unsigned xb_ld(unsigned* p)              { return __hip_atomic_load(p, __ATOMIC_RELAXED, __HIP_MEMORY_SCOPE_AGENT); }
; __device__ __forceinline__ void xcd_barrier_complete(unsigned* bar, unsigned x, unsigned& nloc, unsigned& nx) {
;     ...
;     for (;;) {
;         sum = 0u; cnt = 0u; mine = 0u;
; #pragma unroll
;         for (unsigned j = 0; j < 16; ++j) { const unsigned c = xb_ld(&bar[XB_XCNT(j)]); sum += c; cnt += (c > 0u) ? 1u : 0u; mine = (j == x) ? c : mine; }
;         if (sum == G) break;
;         __builtin_amdgcn_s_sleep(1);
;         if ((++sp & 255u) == 0u) { if (xb_ld(&bar[XB_TMO])) break; if (sp > XB_SPIN_CAP) { atomicAdd(&bar[XB_TMO], 1u); break; } }
;     }
.LBB0_1062:
	global_load_dword v15, v16, s[12:13] sc1
	global_load_dword v0, v16, s[38:39] sc1
	global_load_dword v1, v16, s[42:43] sc1
	global_load_dword v2, v16, s[44:45] sc1
	global_load_dword v3, v16, s[48:49] sc1
	global_load_dword v4, v16, s[50:51] sc1
	global_load_dword v5, v16, s[52:53] sc1
	global_load_dword v6, v16, s[54:55] sc1
	global_load_dword v7, v16, s[56:57] sc1
	global_load_dword v8, v16, s[58:59] sc1
	global_load_dword v9, v16, s[60:61] sc1
	global_load_dword v10, v16, s[62:63] sc1
	global_load_dword v11, v16, s[64:65] sc1
	global_load_dword v12, v16, s[66:67] sc1
	global_load_dword v13, v16, s[82:83] sc1
	global_load_dword v14, v16, s[84:85] sc1
	s_mov_b64 s[86:87], -1
	s_mov_b64 s[88:89], -1
	s_waitcnt vmcnt(14)
	v_add_u32_e32 v17, v0, v15
	s_waitcnt vmcnt(13)
	v_add_u32_e32 v17, v17, v1
	s_waitcnt vmcnt(12)
	v_add_u32_e32 v17, v17, v2
	s_waitcnt vmcnt(11)
	v_add_u32_e32 v17, v17, v3
	s_waitcnt vmcnt(10)
	v_add_u32_e32 v17, v17, v4
	s_waitcnt vmcnt(9)
	v_add_u32_e32 v17, v17, v5
	s_waitcnt vmcnt(8)
	v_add_u32_e32 v17, v17, v6
	s_waitcnt vmcnt(7)
	v_add_u32_e32 v17, v17, v7
	s_waitcnt vmcnt(6)
	v_add_u32_e32 v17, v17, v8
	s_waitcnt vmcnt(5)
	v_add_u32_e32 v17, v17, v9
	s_waitcnt vmcnt(4)
	v_add_u32_e32 v17, v17, v10
	s_waitcnt vmcnt(3)
	v_add_u32_e32 v17, v17, v11
	s_waitcnt vmcnt(2)
	v_add_u32_e32 v17, v17, v12
	s_waitcnt vmcnt(1)
	v_add_u32_e32 v17, v17, v13
	s_waitcnt vmcnt(0)
	v_add_u32_e32 v17, v17, v14
	v_cmp_eq_u32_e32 vcc, s14, v17
	s_cbranch_vccnz .LBB0_1061
	s_and_b32 s15, s3, 0xff
	s_cmp_eq_u32 s15, 0
	s_mov_b64 s[90:91], -1
	s_nop 0
	s_cbranch_scc0 .LBB0_1066
	global_load_dword v17, v16, s[10:11] sc1
	s_waitcnt vmcnt(0)
	v_cmp_eq_u32_e32 vcc, 0, v17
	s_cbranch_vccnz .LBB0_1068
	s_mov_b64 s[90:91], 0

; __device__ __forceinline__ unsigned xb_ld(unsigned* p)              { return __hip_atomic_load(p, __ATOMIC_RELAXED, __HIP_MEMORY_SCOPE_AGENT); }
; __device__ __forceinline__ void xcd_barrier_complete(unsigned* bar, unsigned x, unsigned& nloc, unsigned& nx) {
;     ...
;     for (;;) {
;         sum = 0u; cnt = 0u; mine = 0u;
; #pragma unroll
;         for (unsigned j = 0; j < 16; ++j) { const unsigned c = xb_ld(&bar[XB_XCNT(j)]); sum += c; cnt += (c > 0u) ? 1u : 0u; mine = (j == x) ? c : mine; }
;         if (sum == G) break;
;         __builtin_amdgcn_s_sleep(1);
;         if ((++sp & 255u) == 0u) { if (xb_ld(&bar[XB_TMO])) break; if (sp > XB_SPIN_CAP) { atomicAdd(&bar[XB_TMO], 1u); break; } }
;     }
.LBB0_1130:
	global_load_dword v15, v16, s[12:13] sc1
	global_load_dword v0, v16, s[36:37] sc1
	global_load_dword v1, v16, s[38:39] sc1
	global_load_dword v2, v16, s[42:43] sc1
	global_load_dword v3, v16, s[44:45] sc1
	global_load_dword v4, v16, s[48:49] sc1
	global_load_dword v5, v16, s[50:51] sc1
	global_load_dword v6, v16, s[52:53] sc1
	global_load_dword v7, v16, s[54:55] sc1
	global_load_dword v8, v16, s[56:57] sc1
	global_load_dword v9, v16, s[58:59] sc1
	global_load_dword v10, v16, s[60:61] sc1
	global_load_dword v11, v16, s[62:63] sc1
	global_load_dword v12, v16, s[64:65] sc1
	global_load_dword v13, v16, s[66:67] sc1
	global_load_dword v14, v16, s[82:83] sc1
	s_mov_b64 s[84:85], -1
	s_mov_b64 s[86:87], -1
	s_waitcnt vmcnt(14)
	v_add_u32_e32 v17, v0, v15
	s_waitcnt vmcnt(13)
	v_add_u32_e32 v17, v17, v1
	s_waitcnt vmcnt(12)
	v_add_u32_e32 v17, v17, v2
	s_waitcnt vmcnt(11)
	v_add_u32_e32 v17, v17, v3
	s_waitcnt vmcnt(10)
	v_add_u32_e32 v17, v17, v4
	s_waitcnt vmcnt(9)
	v_add_u32_e32 v17, v17, v5
	s_waitcnt vmcnt(8)
	v_add_u32_e32 v17, v17, v6
	s_waitcnt vmcnt(7)
	v_add_u32_e32 v17, v17, v7
	s_waitcnt vmcnt(6)
	v_add_u32_e32 v17, v17, v8
	s_waitcnt vmcnt(5)
	v_add_u32_e32 v17, v17, v9
	s_waitcnt vmcnt(4)
	v_add_u32_e32 v17, v17, v10
	s_waitcnt vmcnt(3)
	v_add_u32_e32 v17, v17, v11
	s_waitcnt vmcnt(2)
	v_add_u32_e32 v17, v17, v12
	s_waitcnt vmcnt(1)
	v_add_u32_e32 v17, v17, v13
	s_waitcnt vmcnt(0)
	v_add_u32_e32 v17, v17, v14
	v_cmp_eq_u32_e32 vcc, s15, v17
	s_cbranch_vccnz .LBB0_1129
	s_and_b32 s33, s14, 0xff
	s_cmp_eq_u32 s33, 0
	s_mov_b64 s[88:89], -1
	s_nop 0
	s_cbranch_scc0 .LBB0_1134
	global_load_dword v17, v16, s[10:11] sc1
	s_waitcnt vmcnt(0)
	v_cmp_eq_u32_e32 vcc, 0, v17
	s_cbranch_vccnz .LBB0_1136
	s_mov_b64 s[88:89], 0

; __device__ __forceinline__ unsigned xb_ld(unsigned* p)              { return __hip_atomic_load(p, __ATOMIC_RELAXED, __HIP_MEMORY_SCOPE_AGENT); }
; #define XB_SPIN(cond, bar) do { unsigned _sp = 0; while (cond) { __builtin_amdgcn_s_sleep(1); \
;     if ((++_sp & 255u) == 0u) { if (xb_ld(&(bar)[XB_TMO])) break; if (_sp > XB_SPIN_CAP) { atomicAdd(&(bar)[XB_TMO], 1u); break; } } } } while (0)
; __device__ __forceinline__ void xcd_barrier(const XcdBarrier& b) {
;     ...
;             else XB_SPIN(xb_ld(&bar[XB_TOPGEN]) == tg, bar);
.LBB0_1148:
	s_and_b32 s15, s14, 0xff
	s_mov_b64 s[50:51], -1
	s_cmp_lg_u32 s15, 0
	s_mov_b64 s[54:55], -1
	s_nop 0
	s_cbranch_scc1 .LBB0_1151
	global_load_dword v2, v0, s[38:39] sc1
	s_waitcnt vmcnt(0)
	v_cmp_eq_u32_e32 vcc, 0, v2
	s_cbranch_vccnz .LBB0_1153
	s_mov_b64 s[54:55], 0
	s_mov_b64 s[52:53], -1

; __device__ __forceinline__ unsigned xb_ld(unsigned* p)              { return __hip_atomic_load(p, __ATOMIC_RELAXED, __HIP_MEMORY_SCOPE_AGENT); }
; #define XB_SPIN(cond, bar) do { unsigned _sp = 0; while (cond) { __builtin_amdgcn_s_sleep(1); \
;     if ((++_sp & 255u) == 0u) { if (xb_ld(&(bar)[XB_TMO])) break; if (_sp > XB_SPIN_CAP) { atomicAdd(&(bar)[XB_TMO], 1u); break; } } } } while (0)
; __device__ __forceinline__ void xcd_barrier(const XcdBarrier& b) {
;     ...
;             XB_SPIN(xb_ld(&bar[XB_XGEN(b.x)]) == gen, bar);
.LBB0_1165:
	s_and_b32 s15, s14, 0xff
	s_cmp_lg_u32 s15, 0
	s_mov_b64 s[52:53], -1
	s_nop 0
	s_cbranch_scc1 .LBB0_1168
	global_load_dword v1, v0, s[38:39] sc1
	s_waitcnt vmcnt(0)
	v_cmp_eq_u32_e32 vcc, 0, v1
	s_cbranch_vccnz .LBB0_1170
	s_mov_b64 s[52:53], 0
	s_mov_b64 s[50:51], -1

; __device__ __forceinline__ unsigned xb_ld(unsigned* p)              { return __hip_atomic_load(p, __ATOMIC_RELAXED, __HIP_MEMORY_SCOPE_AGENT); }
; __device__ __forceinline__ void xcd_barrier_complete(unsigned* bar, unsigned x, unsigned& nloc, unsigned& nx) {
;     ...
;     for (;;) {
;         sum = 0u; cnt = 0u; mine = 0u;
; #pragma unroll
;         for (unsigned j = 0; j < 16; ++j) { const unsigned c = xb_ld(&bar[XB_XCNT(j)]); sum += c; cnt += (c > 0u) ? 1u : 0u; mine = (j == x) ? c : mine; }
;         if (sum == G) break;
;         __builtin_amdgcn_s_sleep(1);
;         if ((++sp & 255u) == 0u) { if (xb_ld(&bar[XB_TMO])) break; if (sp > XB_SPIN_CAP) { atomicAdd(&bar[XB_TMO], 1u); break; } }
;     }
.LBB0_1224:
	global_load_dword v15, v16, s[12:13] sc1
	global_load_dword v0, v16, s[38:39] sc1
	global_load_dword v1, v16, s[42:43] sc1
	global_load_dword v2, v16, s[44:45] sc1
	global_load_dword v3, v16, s[48:49] sc1
	global_load_dword v4, v16, s[50:51] sc1
	global_load_dword v5, v16, s[52:53] sc1
	global_load_dword v6, v16, s[54:55] sc1
	global_load_dword v7, v16, s[56:57] sc1
	global_load_dword v8, v16, s[58:59] sc1
	global_load_dword v9, v16, s[60:61] sc1
	global_load_dword v10, v16, s[62:63] sc1
	global_load_dword v11, v16, s[64:65] sc1
	global_load_dword v12, v16, s[66:67] sc1
	global_load_dword v13, v16, s[82:83] sc1
	global_load_dword v14, v16, s[84:85] sc1
	s_mov_b64 s[86:87], -1
	s_mov_b64 s[88:89], -1
	s_waitcnt vmcnt(14)
	v_add_u32_e32 v17, v0, v15
	s_waitcnt vmcnt(13)
	v_add_u32_e32 v17, v17, v1
	s_waitcnt vmcnt(12)
	v_add_u32_e32 v17, v17, v2
	s_waitcnt vmcnt(11)
	v_add_u32_e32 v17, v17, v3
	s_waitcnt vmcnt(10)
	v_add_u32_e32 v17, v17, v4
	s_waitcnt vmcnt(9)
	v_add_u32_e32 v17, v17, v5
	s_waitcnt vmcnt(8)
	v_add_u32_e32 v17, v17, v6
	s_waitcnt vmcnt(7)
	v_add_u32_e32 v17, v17, v7
	s_waitcnt vmcnt(6)
	v_add_u32_e32 v17, v17, v8
	s_waitcnt vmcnt(5)
	v_add_u32_e32 v17, v17, v9
	s_waitcnt vmcnt(4)
	v_add_u32_e32 v17, v17, v10
	s_waitcnt vmcnt(3)
	v_add_u32_e32 v17, v17, v11
	s_waitcnt vmcnt(2)
	v_add_u32_e32 v17, v17, v12
	s_waitcnt vmcnt(1)
	v_add_u32_e32 v17, v17, v13
	s_waitcnt vmcnt(0)
	v_add_u32_e32 v17, v17, v14
	v_cmp_eq_u32_e32 vcc, s15, v17
	s_cbranch_vccnz .LBB0_1223
	s_and_b32 s33, s14, 0xff
	s_cmp_eq_u32 s33, 0
	s_mov_b64 s[90:91], -1
	s_nop 0
	s_cbranch_scc0 .LBB0_1228
	global_load_dword v17, v16, s[10:11] sc1
	s_waitcnt vmcnt(0)
	v_cmp_eq_u32_e32 vcc, 0, v17
	s_cbranch_vccnz .LBB0_1230
	s_mov_b64 s[90:91], 0

; __device__ __forceinline__ unsigned xb_ld(unsigned* p)              { return __hip_atomic_load(p, __ATOMIC_RELAXED, __HIP_MEMORY_SCOPE_AGENT); }
; #define XB_SPIN(cond, bar) do { unsigned _sp = 0; while (cond) { __builtin_amdgcn_s_sleep(1); \
;     if ((++_sp & 255u) == 0u) { if (xb_ld(&(bar)[XB_TMO])) break; if (_sp > XB_SPIN_CAP) { atomicAdd(&(bar)[XB_TMO], 1u); break; } } } } while (0)
; __device__ __forceinline__ void xcd_barrier(const XcdBarrier& b) {
;     ...
;             else XB_SPIN(xb_ld(&bar[XB_TOPGEN]) == tg, bar);
.LBB0_1242:
	s_and_b32 s15, s14, 0xff
	s_mov_b64 s[52:53], -1
	s_cmp_lg_u32 s15, 0
	s_mov_b64 s[56:57], -1
	s_nop 0
	s_cbranch_scc1 .LBB0_1245
	global_load_dword v2, v0, s[42:43] sc1
	s_waitcnt vmcnt(0)
	v_cmp_eq_u32_e32 vcc, 0, v2
	s_cbranch_vccnz .LBB0_1247
	s_mov_b64 s[56:57], 0
	s_mov_b64 s[54:55], -1

; __device__ __forceinline__ unsigned xb_ld(unsigned* p)              { return __hip_atomic_load(p, __ATOMIC_RELAXED, __HIP_MEMORY_SCOPE_AGENT); }
; #define XB_SPIN(cond, bar) do { unsigned _sp = 0; while (cond) { __builtin_amdgcn_s_sleep(1); \
;     if ((++_sp & 255u) == 0u) { if (xb_ld(&(bar)[XB_TMO])) break; if (_sp > XB_SPIN_CAP) { atomicAdd(&(bar)[XB_TMO], 1u); break; } } } } while (0)
; __device__ __forceinline__ void xcd_barrier(const XcdBarrier& b) {
;     ...
;             XB_SPIN(xb_ld(&bar[XB_XGEN(b.x)]) == gen, bar);
.LBB0_1259:
	s_and_b32 s15, s14, 0xff
	s_cmp_lg_u32 s15, 0
	s_mov_b64 s[54:55], -1
	s_nop 0
	s_cbranch_scc1 .LBB0_1262
	global_load_dword v1, v0, s[42:43] sc1
	s_waitcnt vmcnt(0)
	v_cmp_eq_u32_e32 vcc, 0, v1
	s_cbranch_vccnz .LBB0_1264
	s_mov_b64 s[54:55], 0
	s_mov_b64 s[52:53], -1

; __device__ __forceinline__ unsigned xb_ld(unsigned* p)              { return __hip_atomic_load(p, __ATOMIC_RELAXED, __HIP_MEMORY_SCOPE_AGENT); }
; __device__ __forceinline__ void xcd_barrier_complete(unsigned* bar, unsigned x, unsigned& nloc, unsigned& nx) {
;     ...
;     for (;;) {
;         sum = 0u; cnt = 0u; mine = 0u;
; #pragma unroll
;         for (unsigned j = 0; j < 16; ++j) { const unsigned c = xb_ld(&bar[XB_XCNT(j)]); sum += c; cnt += (c > 0u) ? 1u : 0u; mine = (j == x) ? c : mine; }
;         if (sum == G) break;
;         __builtin_amdgcn_s_sleep(1);
;         if ((++sp & 255u) == 0u) { if (xb_ld(&bar[XB_TMO])) break; if (sp > XB_SPIN_CAP) { atomicAdd(&bar[XB_TMO], 1u); break; } }
;     }
.LBB0_1318:
	global_load_dword v15, v16, s[36:37] sc1
	global_load_dword v0, v16, s[38:39] sc1
	global_load_dword v1, v16, s[42:43] sc1
	global_load_dword v2, v16, s[44:45] sc1
	global_load_dword v3, v16, s[48:49] sc1
	global_load_dword v4, v16, s[50:51] sc1
	global_load_dword v5, v16, s[52:53] sc1
	global_load_dword v6, v16, s[54:55] sc1
	global_load_dword v7, v16, s[56:57] sc1
	global_load_dword v8, v16, s[58:59] sc1
	global_load_dword v9, v16, s[60:61] sc1
	global_load_dword v10, v16, s[62:63] sc1
	global_load_dword v11, v16, s[64:65] sc1
	global_load_dword v12, v16, s[66:67] sc1
	global_load_dword v13, v16, s[80:81] sc1
	global_load_dword v14, v16, s[82:83] sc1
	s_mov_b64 s[84:85], -1
	s_mov_b64 s[86:87], -1
	s_waitcnt vmcnt(14)
	v_add_u32_e32 v17, v0, v15
	s_waitcnt vmcnt(13)
	v_add_u32_e32 v17, v17, v1
	s_waitcnt vmcnt(12)
	v_add_u32_e32 v17, v17, v2
	s_waitcnt vmcnt(11)
	v_add_u32_e32 v17, v17, v3
	s_waitcnt vmcnt(10)
	v_add_u32_e32 v17, v17, v4
	s_waitcnt vmcnt(9)
	v_add_u32_e32 v17, v17, v5
	s_waitcnt vmcnt(8)
	v_add_u32_e32 v17, v17, v6
	s_waitcnt vmcnt(7)
	v_add_u32_e32 v17, v17, v7
	s_waitcnt vmcnt(6)
	v_add_u32_e32 v17, v17, v8
	s_waitcnt vmcnt(5)
	v_add_u32_e32 v17, v17, v9
	s_waitcnt vmcnt(4)
	v_add_u32_e32 v17, v17, v10
	s_waitcnt vmcnt(3)
	v_add_u32_e32 v17, v17, v11
	s_waitcnt vmcnt(2)
	v_add_u32_e32 v17, v17, v12
	s_waitcnt vmcnt(1)
	v_add_u32_e32 v17, v17, v13
	s_waitcnt vmcnt(0)
	v_add_u32_e32 v17, v17, v14
	v_cmp_eq_u32_e32 vcc, s15, v17
	s_cbranch_vccnz .LBB0_1317
	s_and_b32 s33, s14, 0xff
	s_cmp_eq_u32 s33, 0
	s_mov_b64 s[88:89], -1
	s_nop 0
	s_cbranch_scc0 .LBB0_1322
	global_load_dword v17, v16, s[12:13] sc1
	s_waitcnt vmcnt(0)
	v_cmp_eq_u32_e32 vcc, 0, v17
	s_cbranch_vccnz .LBB0_1324
	s_mov_b64 s[88:89], 0

; __device__ __forceinline__ unsigned xb_ld(unsigned* p)              { return __hip_atomic_load(p, __ATOMIC_RELAXED, __HIP_MEMORY_SCOPE_AGENT); }
; __device__ __forceinline__ void xcd_barrier_complete(unsigned* bar, unsigned x, unsigned& nloc, unsigned& nx) {
;     ...
;     for (;;) {
;         sum = 0u; cnt = 0u; mine = 0u;
; #pragma unroll
;         for (unsigned j = 0; j < 16; ++j) { const unsigned c = xb_ld(&bar[XB_XCNT(j)]); sum += c; cnt += (c > 0u) ? 1u : 0u; mine = (j == x) ? c : mine; }
;         if (sum == G) break;
;         __builtin_amdgcn_s_sleep(1);
;         if ((++sp & 255u) == 0u) { if (xb_ld(&bar[XB_TMO])) break; if (sp > XB_SPIN_CAP) { atomicAdd(&bar[XB_TMO], 1u); break; } }
;     }
.LBB0_1530:
	global_load_dword v15, v16, s[10:11] sc1
	global_load_dword v0, v16, s[12:13] sc1
	global_load_dword v1, v16, s[26:27] sc1
	global_load_dword v2, v16, s[28:29] sc1
	global_load_dword v3, v16, s[36:37] sc1
	global_load_dword v4, v16, s[38:39] sc1
	global_load_dword v5, v16, s[42:43] sc1
	global_load_dword v6, v16, s[44:45] sc1
	global_load_dword v7, v16, s[46:47] sc1
	global_load_dword v8, v16, s[48:49] sc1
	global_load_dword v9, v16, s[50:51] sc1
	global_load_dword v10, v16, s[52:53] sc1
	global_load_dword v11, v16, s[54:55] sc1
	global_load_dword v12, v16, s[56:57] sc1
	global_load_dword v13, v16, s[58:59] sc1
	global_load_dword v14, v16, s[60:61] sc1
	s_mov_b64 s[62:63], -1
	s_mov_b64 s[64:65], -1
	s_waitcnt vmcnt(14)
	v_add_u32_e32 v17, v0, v15
	s_waitcnt vmcnt(13)
	v_add_u32_e32 v17, v17, v1
	s_waitcnt vmcnt(12)
	v_add_u32_e32 v17, v17, v2
	s_waitcnt vmcnt(11)
	v_add_u32_e32 v17, v17, v3
	s_waitcnt vmcnt(10)
	v_add_u32_e32 v17, v17, v4
	s_waitcnt vmcnt(9)
	v_add_u32_e32 v17, v17, v5
	s_waitcnt vmcnt(8)
	v_add_u32_e32 v17, v17, v6
	s_waitcnt vmcnt(7)
	v_add_u32_e32 v17, v17, v7
	s_waitcnt vmcnt(6)
	v_add_u32_e32 v17, v17, v8
	s_waitcnt vmcnt(5)
	v_add_u32_e32 v17, v17, v9
	s_waitcnt vmcnt(4)
	v_add_u32_e32 v17, v17, v10
	s_waitcnt vmcnt(3)
	v_add_u32_e32 v17, v17, v11
	s_waitcnt vmcnt(2)
	v_add_u32_e32 v17, v17, v12
	s_waitcnt vmcnt(1)
	v_add_u32_e32 v17, v17, v13
	s_waitcnt vmcnt(0)
	v_add_u32_e32 v17, v17, v14
	v_cmp_eq_u32_e32 vcc, s33, v17
	s_cbranch_vccnz .LBB0_1529
	s_and_b32 s34, s15, 0xff
	s_cmp_eq_u32 s34, 0
	s_mov_b64 s[66:67], -1
	s_nop 0
	s_cbranch_scc0 .LBB0_1534
	global_load_dword v17, v16, s[4:5] sc1
	s_waitcnt vmcnt(0)
	v_cmp_eq_u32_e32 vcc, 0, v17
	s_cbranch_vccnz .LBB0_1536
	s_mov_b64 s[66:67], 0

; __device__ __forceinline__ unsigned xb_ld(unsigned* p)              { return __hip_atomic_load(p, __ATOMIC_RELAXED, __HIP_MEMORY_SCOPE_AGENT); }
; #define XB_SPIN(cond, bar) do { unsigned _sp = 0; while (cond) { __builtin_amdgcn_s_sleep(1); \
;     if ((++_sp & 255u) == 0u) { if (xb_ld(&(bar)[XB_TMO])) break; if (_sp > XB_SPIN_CAP) { atomicAdd(&(bar)[XB_TMO], 1u); break; } } } } while (0)
; __device__ __forceinline__ void xcd_barrier(const XcdBarrier& b) {
;     ...
;             else XB_SPIN(xb_ld(&bar[XB_TOPGEN]) == tg, bar);
.LBB0_1548:
	s_and_b32 s33, s15, 0xff
	s_mov_b64 s[42:43], -1
	s_cmp_lg_u32 s33, 0
	s_mov_b64 s[46:47], -1
	s_nop 0
	s_cbranch_scc1 .LBB0_1551
	global_load_dword v2, v0, s[26:27] sc1
	s_waitcnt vmcnt(0)
	v_cmp_eq_u32_e32 vcc, 0, v2
	s_cbranch_vccnz .LBB0_1553
	s_mov_b64 s[46:47], 0
	s_mov_b64 s[44:45], -1

; __device__ __forceinline__ unsigned xb_ld(unsigned* p)              { return __hip_atomic_load(p, __ATOMIC_RELAXED, __HIP_MEMORY_SCOPE_AGENT); }
; #define XB_SPIN(cond, bar) do { unsigned _sp = 0; while (cond) { __builtin_amdgcn_s_sleep(1); \
;     if ((++_sp & 255u) == 0u) { if (xb_ld(&(bar)[XB_TMO])) break; if (_sp > XB_SPIN_CAP) { atomicAdd(&(bar)[XB_TMO], 1u); break; } } } } while (0)
; __device__ __forceinline__ void xcd_barrier(const XcdBarrier& b) {
;     ...
;             XB_SPIN(xb_ld(&bar[XB_XGEN(b.x)]) == gen, bar);
.LBB0_1565:
	s_and_b32 s33, s15, 0xff
	s_cmp_lg_u32 s33, 0
	s_mov_b64 s[44:45], -1
	s_nop 0
	s_cbranch_scc1 .LBB0_1568
	global_load_dword v1, v0, s[26:27] sc1
	s_waitcnt vmcnt(0)
	v_cmp_eq_u32_e32 vcc, 0, v1
	s_cbranch_vccnz .LBB0_1570
	s_mov_b64 s[44:45], 0
	s_mov_b64 s[42:43], -1

; __device__ __forceinline__ unsigned xb_ld(unsigned* p)              { return __hip_atomic_load(p, __ATOMIC_RELAXED, __HIP_MEMORY_SCOPE_AGENT); }
; __device__ __forceinline__ void xcd_barrier_complete(unsigned* bar, unsigned x, unsigned& nloc, unsigned& nx) {
;     ...
;     for (;;) {
;         sum = 0u; cnt = 0u; mine = 0u;
; #pragma unroll
;         for (unsigned j = 0; j < 16; ++j) { const unsigned c = xb_ld(&bar[XB_XCNT(j)]); sum += c; cnt += (c > 0u) ? 1u : 0u; mine = (j == x) ? c : mine; }
;         if (sum == G) break;
;         __builtin_amdgcn_s_sleep(1);
;         if ((++sp & 255u) == 0u) { if (xb_ld(&bar[XB_TMO])) break; if (sp > XB_SPIN_CAP) { atomicAdd(&bar[XB_TMO], 1u); break; } }
;     }
.LBB0_1620:
	global_load_dword v15, v16, s[10:11] sc1
	global_load_dword v0, v16, s[26:27] sc1
	global_load_dword v1, v16, s[28:29] sc1
	global_load_dword v2, v16, s[36:37] sc1
	global_load_dword v3, v16, s[38:39] sc1
	global_load_dword v4, v16, s[40:41] sc1
	global_load_dword v5, v16, s[42:43] sc1
	global_load_dword v6, v16, s[44:45] sc1
	global_load_dword v7, v16, s[46:47] sc1
	global_load_dword v8, v16, s[48:49] sc1
	global_load_dword v9, v16, s[50:51] sc1
	global_load_dword v10, v16, s[52:53] sc1
	global_load_dword v11, v16, s[54:55] sc1
	global_load_dword v12, v16, s[56:57] sc1
	global_load_dword v13, v16, s[58:59] sc1
	global_load_dword v14, v16, s[60:61] sc1
	s_mov_b64 s[62:63], -1
	s_mov_b64 s[64:65], -1
	s_waitcnt vmcnt(14)
	v_add_u32_e32 v17, v0, v15
	s_waitcnt vmcnt(13)
	v_add_u32_e32 v17, v17, v1
	s_waitcnt vmcnt(12)
	v_add_u32_e32 v17, v17, v2
	s_waitcnt vmcnt(11)
	v_add_u32_e32 v17, v17, v3
	s_waitcnt vmcnt(10)
	v_add_u32_e32 v17, v17, v4
	s_waitcnt vmcnt(9)
	v_add_u32_e32 v17, v17, v5
	s_waitcnt vmcnt(8)
	v_add_u32_e32 v17, v17, v6
	s_waitcnt vmcnt(7)
	v_add_u32_e32 v17, v17, v7
	s_waitcnt vmcnt(6)
	v_add_u32_e32 v17, v17, v8
	s_waitcnt vmcnt(5)
	v_add_u32_e32 v17, v17, v9
	s_waitcnt vmcnt(4)
	v_add_u32_e32 v17, v17, v10
	s_waitcnt vmcnt(3)
	v_add_u32_e32 v17, v17, v11
	s_waitcnt vmcnt(2)
	v_add_u32_e32 v17, v17, v12
	s_waitcnt vmcnt(1)
	v_add_u32_e32 v17, v17, v13
	s_waitcnt vmcnt(0)
	v_add_u32_e32 v17, v17, v14
	v_cmp_eq_u32_e32 vcc, s33, v17
	s_cbranch_vccnz .LBB0_1619
	s_and_b32 s34, s15, 0xff
	s_cmp_eq_u32 s34, 0
	s_mov_b64 s[66:67], -1
	s_nop 0
	s_cbranch_scc0 .LBB0_1624
	global_load_dword v17, v16, s[4:5] sc1
	s_waitcnt vmcnt(0)
	v_cmp_eq_u32_e32 vcc, 0, v17
	s_cbranch_vccnz .LBB0_1626
	s_mov_b64 s[66:67], 0

; __device__ __forceinline__ unsigned xb_ld(unsigned* p)              { return __hip_atomic_load(p, __ATOMIC_RELAXED, __HIP_MEMORY_SCOPE_AGENT); }
; #define XB_SPIN(cond, bar) do { unsigned _sp = 0; while (cond) { __builtin_amdgcn_s_sleep(1); \
;     if ((++_sp & 255u) == 0u) { if (xb_ld(&(bar)[XB_TMO])) break; if (_sp > XB_SPIN_CAP) { atomicAdd(&(bar)[XB_TMO], 1u); break; } } } } while (0)
; __device__ __forceinline__ void xcd_barrier(const XcdBarrier& b) {
;     ...
;             else XB_SPIN(xb_ld(&bar[XB_TOPGEN]) == tg, bar);
.LBB0_1638:
	s_and_b32 s33, s15, 0xff
	s_mov_b64 s[42:43], -1
	s_cmp_lg_u32 s33, 0
	s_mov_b64 s[46:47], -1
	s_nop 0
	s_cbranch_scc1 .LBB0_1641
	global_load_dword v2, v0, s[28:29] sc1
	s_waitcnt vmcnt(0)
	v_cmp_eq_u32_e32 vcc, 0, v2
	s_cbranch_vccnz .LBB0_1643
	s_mov_b64 s[46:47], 0
	s_mov_b64 s[44:45], -1

; __device__ __forceinline__ unsigned xb_ld(unsigned* p)              { return __hip_atomic_load(p, __ATOMIC_RELAXED, __HIP_MEMORY_SCOPE_AGENT); }
; #define XB_SPIN(cond, bar) do { unsigned _sp = 0; while (cond) { __builtin_amdgcn_s_sleep(1); \
;     if ((++_sp & 255u) == 0u) { if (xb_ld(&(bar)[XB_TMO])) break; if (_sp > XB_SPIN_CAP) { atomicAdd(&(bar)[XB_TMO], 1u); break; } } } } while (0)
; __device__ __forceinline__ void xcd_barrier(const XcdBarrier& b) {
;     ...
;             XB_SPIN(xb_ld(&bar[XB_XGEN(b.x)]) == gen, bar);
.LBB0_1655:
	s_and_b32 s33, s15, 0xff
	s_cmp_lg_u32 s33, 0
	s_mov_b64 s[44:45], -1
	s_nop 0
	s_cbranch_scc1 .LBB0_1658
	global_load_dword v1, v0, s[28:29] sc1
	s_waitcnt vmcnt(0)
	v_cmp_eq_u32_e32 vcc, 0, v1
	s_cbranch_vccnz .LBB0_1660
	s_mov_b64 s[44:45], 0
	s_mov_b64 s[42:43], -1

; __device__ __forceinline__ unsigned xb_ld(unsigned* p)              { return __hip_atomic_load(p, __ATOMIC_RELAXED, __HIP_MEMORY_SCOPE_AGENT); }
; __device__ __forceinline__ void xcd_barrier_complete(unsigned* bar, unsigned x, unsigned& nloc, unsigned& nx) {
;     ...
;     for (;;) {
;         sum = 0u; cnt = 0u; mine = 0u;
; #pragma unroll
;         for (unsigned j = 0; j < 16; ++j) { const unsigned c = xb_ld(&bar[XB_XCNT(j)]); sum += c; cnt += (c > 0u) ? 1u : 0u; mine = (j == x) ? c : mine; }
;         if (sum == G) break;
;         __builtin_amdgcn_s_sleep(1);
;         if ((++sp & 255u) == 0u) { if (xb_ld(&bar[XB_TMO])) break; if (sp > XB_SPIN_CAP) { atomicAdd(&bar[XB_TMO], 1u); break; } }
;     }
.LBB0_1692:
	global_load_dword v15, v16, s[10:11] sc1
	global_load_dword v0, v16, s[12:13] sc1
	global_load_dword v1, v16, s[26:27] sc1
	global_load_dword v2, v16, s[28:29] sc1
	global_load_dword v3, v16, s[36:37] sc1
	global_load_dword v4, v16, s[38:39] sc1
	global_load_dword v5, v16, s[40:41] sc1
	global_load_dword v6, v16, s[42:43] sc1
	global_load_dword v7, v16, s[44:45] sc1
	global_load_dword v8, v16, s[46:47] sc1
	global_load_dword v9, v16, s[48:49] sc1
	global_load_dword v10, v16, s[50:51] sc1
	global_load_dword v11, v16, s[52:53] sc1
	global_load_dword v12, v16, s[54:55] sc1
	global_load_dword v13, v16, s[56:57] sc1
	global_load_dword v14, v16, s[58:59] sc1
	s_mov_b64 s[60:61], -1
	s_mov_b64 s[62:63], -1
	s_waitcnt vmcnt(14)
	v_add_u32_e32 v17, v0, v15
	s_waitcnt vmcnt(13)
	v_add_u32_e32 v17, v17, v1
	s_waitcnt vmcnt(12)
	v_add_u32_e32 v17, v17, v2
	s_waitcnt vmcnt(11)
	v_add_u32_e32 v17, v17, v3
	s_waitcnt vmcnt(10)
	v_add_u32_e32 v17, v17, v4
	s_waitcnt vmcnt(9)
	v_add_u32_e32 v17, v17, v5
	s_waitcnt vmcnt(8)
	v_add_u32_e32 v17, v17, v6
	s_waitcnt vmcnt(7)
	v_add_u32_e32 v17, v17, v7
	s_waitcnt vmcnt(6)
	v_add_u32_e32 v17, v17, v8
	s_waitcnt vmcnt(5)
	v_add_u32_e32 v17, v17, v9
	s_waitcnt vmcnt(4)
	v_add_u32_e32 v17, v17, v10
	s_waitcnt vmcnt(3)
	v_add_u32_e32 v17, v17, v11
	s_waitcnt vmcnt(2)
	v_add_u32_e32 v17, v17, v12
	s_waitcnt vmcnt(1)
	v_add_u32_e32 v17, v17, v13
	s_waitcnt vmcnt(0)
	v_add_u32_e32 v17, v17, v14
	v_cmp_eq_u32_e32 vcc, s33, v17
	s_cbranch_vccnz .LBB0_1691
	s_and_b32 s34, s15, 0xff
	s_cmp_eq_u32 s34, 0
	s_mov_b64 s[64:65], -1
	s_nop 0
	s_cbranch_scc0 .LBB0_1696
	global_load_dword v17, v16, s[4:5] sc1
	s_waitcnt vmcnt(0)
	v_cmp_eq_u32_e32 vcc, 0, v17
	s_cbranch_vccnz .LBB0_1698
	s_mov_b64 s[64:65], 0

; __device__ __forceinline__ unsigned xb_ld(unsigned* p)              { return __hip_atomic_load(p, __ATOMIC_RELAXED, __HIP_MEMORY_SCOPE_AGENT); }
; #define XB_SPIN(cond, bar) do { unsigned _sp = 0; while (cond) { __builtin_amdgcn_s_sleep(1); \
;     if ((++_sp & 255u) == 0u) { if (xb_ld(&(bar)[XB_TMO])) break; if (_sp > XB_SPIN_CAP) { atomicAdd(&(bar)[XB_TMO], 1u); break; } } } } while (0)
; __device__ __forceinline__ void xcd_barrier(const XcdBarrier& b) {
;     ...
;             else XB_SPIN(xb_ld(&bar[XB_TOPGEN]) == tg, bar);
.LBB0_1710:
	s_and_b32 s33, s15, 0xff
	s_mov_b64 s[40:41], -1
	s_cmp_lg_u32 s33, 0
	s_mov_b64 s[44:45], -1
	s_nop 0
	s_cbranch_scc1 .LBB0_1713
	global_load_dword v2, v0, s[26:27] sc1
	s_waitcnt vmcnt(0)
	v_cmp_eq_u32_e32 vcc, 0, v2
	s_cbranch_vccnz .LBB0_1715
	s_mov_b64 s[44:45], 0
	s_mov_b64 s[42:43], -1

; __device__ __forceinline__ unsigned xb_ld(unsigned* p)              { return __hip_atomic_load(p, __ATOMIC_RELAXED, __HIP_MEMORY_SCOPE_AGENT); }
; #define XB_SPIN(cond, bar) do { unsigned _sp = 0; while (cond) { __builtin_amdgcn_s_sleep(1); \
;     if ((++_sp & 255u) == 0u) { if (xb_ld(&(bar)[XB_TMO])) break; if (_sp > XB_SPIN_CAP) { atomicAdd(&(bar)[XB_TMO], 1u); break; } } } } while (0)
; __device__ __forceinline__ void xcd_barrier(const XcdBarrier& b) {
;     ...
;             XB_SPIN(xb_ld(&bar[XB_XGEN(b.x)]) == gen, bar);
.LBB0_1727:
	s_and_b32 s33, s15, 0xff
	s_cmp_lg_u32 s33, 0
	s_mov_b64 s[42:43], -1
	s_nop 0
	s_cbranch_scc1 .LBB0_1730
	global_load_dword v1, v0, s[26:27] sc1
	s_waitcnt vmcnt(0)
	v_cmp_eq_u32_e32 vcc, 0, v1
	s_cbranch_vccnz .LBB0_1732
	s_mov_b64 s[42:43], 0
	s_mov_b64 s[40:41], -1

; __device__ __forceinline__ unsigned xb_ld(unsigned* p)              { return __hip_atomic_load(p, __ATOMIC_RELAXED, __HIP_MEMORY_SCOPE_AGENT); }
; __device__ __forceinline__ void xcd_barrier_complete(unsigned* bar, unsigned x, unsigned& nloc, unsigned& nx) {
;     ...
;     for (;;) {
;         sum = 0u; cnt = 0u; mine = 0u;
; #pragma unroll
;         for (unsigned j = 0; j < 16; ++j) { const unsigned c = xb_ld(&bar[XB_XCNT(j)]); sum += c; cnt += (c > 0u) ? 1u : 0u; mine = (j == x) ? c : mine; }
;         if (sum == G) break;
;         __builtin_amdgcn_s_sleep(1);
;         if ((++sp & 255u) == 0u) { if (xb_ld(&bar[XB_TMO])) break; if (sp > XB_SPIN_CAP) { atomicAdd(&bar[XB_TMO], 1u); break; } }
;     }
.LBB0_1753:
	global_load_dword v15, v16, s[6:7] sc1
	global_load_dword v0, v16, s[10:11] sc1
	global_load_dword v1, v16, s[12:13] sc1
	global_load_dword v2, v16, s[24:25] sc1
	global_load_dword v3, v16, s[26:27] sc1
	global_load_dword v4, v16, s[28:29] sc1
	global_load_dword v5, v16, s[36:37] sc1
	global_load_dword v6, v16, s[38:39] sc1
	global_load_dword v7, v16, s[40:41] sc1
	global_load_dword v8, v16, s[42:43] sc1
	global_load_dword v9, v16, s[44:45] sc1
	global_load_dword v10, v16, s[46:47] sc1
	global_load_dword v11, v16, s[48:49] sc1
	global_load_dword v12, v16, s[50:51] sc1
	global_load_dword v13, v16, s[52:53] sc1
	global_load_dword v14, v16, s[54:55] sc1
	s_mov_b64 s[56:57], -1
	s_mov_b64 s[58:59], -1
	s_waitcnt vmcnt(14)
	v_add_u32_e32 v17, v0, v15
	s_waitcnt vmcnt(13)
	v_add_u32_e32 v17, v17, v1
	s_waitcnt vmcnt(12)
	v_add_u32_e32 v17, v17, v2
	s_waitcnt vmcnt(11)
	v_add_u32_e32 v17, v17, v3
	s_waitcnt vmcnt(10)
	v_add_u32_e32 v17, v17, v4
	s_waitcnt vmcnt(9)
	v_add_u32_e32 v17, v17, v5
	s_waitcnt vmcnt(8)
	v_add_u32_e32 v17, v17, v6
	s_waitcnt vmcnt(7)
	v_add_u32_e32 v17, v17, v7
	s_waitcnt vmcnt(6)
	v_add_u32_e32 v17, v17, v8
	s_waitcnt vmcnt(5)
	v_add_u32_e32 v17, v17, v9
	s_waitcnt vmcnt(4)
	v_add_u32_e32 v17, v17, v10
	s_waitcnt vmcnt(3)
	v_add_u32_e32 v17, v17, v11
	s_waitcnt vmcnt(2)
	v_add_u32_e32 v17, v17, v12
	s_waitcnt vmcnt(1)
	v_add_u32_e32 v17, v17, v13
	s_waitcnt vmcnt(0)
	v_add_u32_e32 v17, v17, v14
	v_cmp_eq_u32_e32 vcc, s14, v17
	s_cbranch_vccnz .LBB0_1752
	s_and_b32 s15, s3, 0xff
	s_cmp_eq_u32 s15, 0
	s_mov_b64 s[60:61], -1
	s_nop 0
	s_cbranch_scc0 .LBB0_1757
	global_load_dword v17, v16, s[4:5] sc1
	s_waitcnt vmcnt(0)
	v_cmp_eq_u32_e32 vcc, 0, v17
	s_cbranch_vccnz .LBB0_1759
	s_mov_b64 s[60:61], 0

; __device__ __forceinline__ unsigned xb_ld(unsigned* p)              { return __hip_atomic_load(p, __ATOMIC_RELAXED, __HIP_MEMORY_SCOPE_AGENT); }
; #define XB_SPIN(cond, bar) do { unsigned _sp = 0; while (cond) { __builtin_amdgcn_s_sleep(1); \
;     if ((++_sp & 255u) == 0u) { if (xb_ld(&(bar)[XB_TMO])) break; if (_sp > XB_SPIN_CAP) { atomicAdd(&(bar)[XB_TMO], 1u); break; } } } } while (0)
; __device__ __forceinline__ void xcd_barrier(const XcdBarrier& b) {
;     ...
;             else XB_SPIN(xb_ld(&bar[XB_TOPGEN]) == tg, bar);
.LBB0_1771:
	s_and_b32 s14, s3, 0xff
	s_mov_b64 s[36:37], -1
	s_cmp_lg_u32 s14, 0
	s_mov_b64 s[40:41], -1
	s_nop 0
	s_cbranch_scc1 .LBB0_1774
	global_load_dword v2, v0, s[12:13] sc1
	s_waitcnt vmcnt(0)
	v_cmp_eq_u32_e32 vcc, 0, v2
	s_cbranch_vccnz .LBB0_1776
	s_mov_b64 s[40:41], 0
	s_mov_b64 s[38:39], -1

; __device__ __forceinline__ unsigned xb_ld(unsigned* p)              { return __hip_atomic_load(p, __ATOMIC_RELAXED, __HIP_MEMORY_SCOPE_AGENT); }
; #define XB_SPIN(cond, bar) do { unsigned _sp = 0; while (cond) { __builtin_amdgcn_s_sleep(1); \
;     if ((++_sp & 255u) == 0u) { if (xb_ld(&(bar)[XB_TMO])) break; if (_sp > XB_SPIN_CAP) { atomicAdd(&(bar)[XB_TMO], 1u); break; } } } } while (0)
; __device__ __forceinline__ void xcd_barrier(const XcdBarrier& b) {
;     ...
;             XB_SPIN(xb_ld(&bar[XB_XGEN(b.x)]) == gen, bar);
.LBB0_1788:
	s_and_b32 s14, s3, 0xff
	s_cmp_lg_u32 s14, 0
	s_mov_b64 s[38:39], -1
	s_nop 0
	s_cbranch_scc1 .LBB0_1791
	global_load_dword v1, v0, s[12:13] sc1
	s_waitcnt vmcnt(0)
	v_cmp_eq_u32_e32 vcc, 0, v1
	s_cbranch_vccnz .LBB0_1793
	s_mov_b64 s[38:39], 0
	s_mov_b64 s[36:37], -1

; __device__ __forceinline__ unsigned xb_ld(unsigned* p)              { return __hip_atomic_load(p, __ATOMIC_RELAXED, __HIP_MEMORY_SCOPE_AGENT); }
; __device__ __forceinline__ void xcd_barrier_complete(unsigned* bar, unsigned x, unsigned& nloc, unsigned& nx) {
;     ...
;     for (;;) {
;         sum = 0u; cnt = 0u; mine = 0u;
; #pragma unroll
;         for (unsigned j = 0; j < 16; ++j) { const unsigned c = xb_ld(&bar[XB_XCNT(j)]); sum += c; cnt += (c > 0u) ? 1u : 0u; mine = (j == x) ? c : mine; }
;         if (sum == G) break;
;         __builtin_amdgcn_s_sleep(1);
;         if ((++sp & 255u) == 0u) { if (xb_ld(&bar[XB_TMO])) break; if (sp > XB_SPIN_CAP) { atomicAdd(&bar[XB_TMO], 1u); break; } }
;     }
.LBB0_1843:
	global_load_dword v15, v16, s[10:11] sc1
	global_load_dword v0, v16, s[12:13] sc1
	global_load_dword v1, v16, s[24:25] sc1
	global_load_dword v2, v16, s[26:27] sc1
	global_load_dword v3, v16, s[28:29] sc1
	global_load_dword v4, v16, s[36:37] sc1
	global_load_dword v5, v16, s[38:39] sc1
	global_load_dword v6, v16, s[40:41] sc1
	global_load_dword v7, v16, s[42:43] sc1
	global_load_dword v8, v16, s[44:45] sc1
	global_load_dword v9, v16, s[46:47] sc1
	global_load_dword v10, v16, s[48:49] sc1
	global_load_dword v11, v16, s[50:51] sc1
	global_load_dword v12, v16, s[52:53] sc1
	global_load_dword v13, v16, s[54:55] sc1
	global_load_dword v14, v16, s[56:57] sc1
	s_mov_b64 s[58:59], -1
	s_mov_b64 s[60:61], -1
	s_waitcnt vmcnt(14)
	v_add_u32_e32 v17, v0, v15
	s_waitcnt vmcnt(13)
	v_add_u32_e32 v17, v17, v1
	s_waitcnt vmcnt(12)
	v_add_u32_e32 v17, v17, v2
	s_waitcnt vmcnt(11)
	v_add_u32_e32 v17, v17, v3
	s_waitcnt vmcnt(10)
	v_add_u32_e32 v17, v17, v4
	s_waitcnt vmcnt(9)
	v_add_u32_e32 v17, v17, v5
	s_waitcnt vmcnt(8)
	v_add_u32_e32 v17, v17, v6
	s_waitcnt vmcnt(7)
	v_add_u32_e32 v17, v17, v7
	s_waitcnt vmcnt(6)
	v_add_u32_e32 v17, v17, v8
	s_waitcnt vmcnt(5)
	v_add_u32_e32 v17, v17, v9
	s_waitcnt vmcnt(4)
	v_add_u32_e32 v17, v17, v10
	s_waitcnt vmcnt(3)
	v_add_u32_e32 v17, v17, v11
	s_waitcnt vmcnt(2)
	v_add_u32_e32 v17, v17, v12
	s_waitcnt vmcnt(1)
	v_add_u32_e32 v17, v17, v13
	s_waitcnt vmcnt(0)
	v_add_u32_e32 v17, v17, v14
	v_cmp_eq_u32_e32 vcc, s14, v17
	s_cbranch_vccnz .LBB0_1842
	s_and_b32 s15, s3, 0xff
	s_cmp_eq_u32 s15, 0
	s_mov_b64 s[62:63], -1
	s_nop 0
	s_cbranch_scc0 .LBB0_1847
	global_load_dword v17, v16, s[6:7] sc1
	s_waitcnt vmcnt(0)
	v_cmp_eq_u32_e32 vcc, 0, v17
	s_cbranch_vccnz .LBB0_1849
	s_mov_b64 s[62:63], 0

; __device__ __forceinline__ unsigned xb_ld(unsigned* p)              { return __hip_atomic_load(p, __ATOMIC_RELAXED, __HIP_MEMORY_SCOPE_AGENT); }
; #define XB_SPIN(cond, bar) do { unsigned _sp = 0; while (cond) { __builtin_amdgcn_s_sleep(1); \
;     if ((++_sp & 255u) == 0u) { if (xb_ld(&(bar)[XB_TMO])) break; if (_sp > XB_SPIN_CAP) { atomicAdd(&(bar)[XB_TMO], 1u); break; } } } } while (0)
; __device__ __forceinline__ void xcd_barrier(const XcdBarrier& b) {
;     ...
;             else XB_SPIN(xb_ld(&bar[XB_TOPGEN]) == tg, bar);
.LBB0_1861:
	s_and_b32 s14, s3, 0xff
	s_mov_b64 s[38:39], -1
	s_cmp_lg_u32 s14, 0
	s_mov_b64 s[42:43], -1
	s_nop 0
	s_cbranch_scc1 .LBB0_1864
	global_load_dword v2, v0, s[24:25] sc1
	s_waitcnt vmcnt(0)
	v_cmp_eq_u32_e32 vcc, 0, v2
	s_cbranch_vccnz .LBB0_1866
	s_mov_b64 s[42:43], 0
	s_mov_b64 s[40:41], -1

; __device__ __forceinline__ unsigned xb_ld(unsigned* p)              { return __hip_atomic_load(p, __ATOMIC_RELAXED, __HIP_MEMORY_SCOPE_AGENT); }
; #define XB_SPIN(cond, bar) do { unsigned _sp = 0; while (cond) { __builtin_amdgcn_s_sleep(1); \
;     if ((++_sp & 255u) == 0u) { if (xb_ld(&(bar)[XB_TMO])) break; if (_sp > XB_SPIN_CAP) { atomicAdd(&(bar)[XB_TMO], 1u); break; } } } } while (0)
; __device__ __forceinline__ void xcd_barrier(const XcdBarrier& b) {
;     ...
;             XB_SPIN(xb_ld(&bar[XB_XGEN(b.x)]) == gen, bar);
.LBB0_1878:
	s_and_b32 s14, s3, 0xff
	s_cmp_lg_u32 s14, 0
	s_mov_b64 s[40:41], -1
	s_nop 0
	s_cbranch_scc1 .LBB0_1881
	global_load_dword v1, v0, s[24:25] sc1
	s_waitcnt vmcnt(0)
	v_cmp_eq_u32_e32 vcc, 0, v1
	s_cbranch_vccnz .LBB0_1883
	s_mov_b64 s[40:41], 0
	s_mov_b64 s[38:39], -1

; __device__ __forceinline__ unsigned xb_ld(unsigned* p)              { return __hip_atomic_load(p, __ATOMIC_RELAXED, __HIP_MEMORY_SCOPE_AGENT); }
; __device__ __forceinline__ void xcd_barrier_complete(unsigned* bar, unsigned x, unsigned& nloc, unsigned& nx) {
;     ...
;     for (;;) {
;         sum = 0u; cnt = 0u; mine = 0u;
; #pragma unroll
;         for (unsigned j = 0; j < 16; ++j) { const unsigned c = xb_ld(&bar[XB_XCNT(j)]); sum += c; cnt += (c > 0u) ? 1u : 0u; mine = (j == x) ? c : mine; }
;         if (sum == G) break;
;         __builtin_amdgcn_s_sleep(1);
;         if ((++sp & 255u) == 0u) { if (xb_ld(&bar[XB_TMO])) break; if (sp > XB_SPIN_CAP) { atomicAdd(&bar[XB_TMO], 1u); break; } }
;     }
.LBB0_1911:
	global_load_dword v15, v16, s[6:7] sc1
	global_load_dword v0, v16, s[8:9] sc1
	global_load_dword v1, v16, s[10:11] sc1
	global_load_dword v2, v16, s[12:13] sc1
	global_load_dword v3, v16, s[24:25] sc1
	global_load_dword v4, v16, s[26:27] sc1
	global_load_dword v5, v16, s[28:29] sc1
	global_load_dword v6, v16, s[36:37] sc1
	global_load_dword v7, v16, s[38:39] sc1
	global_load_dword v8, v16, s[40:41] sc1
	global_load_dword v9, v16, s[42:43] sc1
	global_load_dword v10, v16, s[44:45] sc1
	global_load_dword v11, v16, s[46:47] sc1
	global_load_dword v12, v16, s[48:49] sc1
	global_load_dword v13, v16, s[50:51] sc1
	global_load_dword v14, v16, s[52:53] sc1
	s_mov_b64 s[54:55], -1
	s_mov_b64 s[56:57], -1
	s_waitcnt vmcnt(14)
	v_add_u32_e32 v17, v0, v15
	s_waitcnt vmcnt(13)
	v_add_u32_e32 v17, v17, v1
	s_waitcnt vmcnt(12)
	v_add_u32_e32 v17, v17, v2
	s_waitcnt vmcnt(11)
	v_add_u32_e32 v17, v17, v3
	s_waitcnt vmcnt(10)
	v_add_u32_e32 v17, v17, v4
	s_waitcnt vmcnt(9)
	v_add_u32_e32 v17, v17, v5
	s_waitcnt vmcnt(8)
	v_add_u32_e32 v17, v17, v6
	s_waitcnt vmcnt(7)
	v_add_u32_e32 v17, v17, v7
	s_waitcnt vmcnt(6)
	v_add_u32_e32 v17, v17, v8
	s_waitcnt vmcnt(5)
	v_add_u32_e32 v17, v17, v9
	s_waitcnt vmcnt(4)
	v_add_u32_e32 v17, v17, v10
	s_waitcnt vmcnt(3)
	v_add_u32_e32 v17, v17, v11
	s_waitcnt vmcnt(2)
	v_add_u32_e32 v17, v17, v12
	s_waitcnt vmcnt(1)
	v_add_u32_e32 v17, v17, v13
	s_waitcnt vmcnt(0)
	v_add_u32_e32 v17, v17, v14
	v_cmp_eq_u32_e32 vcc, s14, v17
	s_cbranch_vccnz .LBB0_1910
	s_and_b32 s15, s3, 0xff
	s_cmp_eq_u32 s15, 0
	s_mov_b64 s[58:59], -1
	s_nop 0
	s_cbranch_scc0 .LBB0_1915
	global_load_dword v17, v16, s[4:5] sc1
	s_waitcnt vmcnt(0)
	v_cmp_eq_u32_e32 vcc, 0, v17
	s_cbranch_vccnz .LBB0_1917
	s_mov_b64 s[58:59], 0

; __device__ __forceinline__ unsigned xb_ld(unsigned* p)              { return __hip_atomic_load(p, __ATOMIC_RELAXED, __HIP_MEMORY_SCOPE_AGENT); }
; #define XB_SPIN(cond, bar) do { unsigned _sp = 0; while (cond) { __builtin_amdgcn_s_sleep(1); \
;     if ((++_sp & 255u) == 0u) { if (xb_ld(&(bar)[XB_TMO])) break; if (_sp > XB_SPIN_CAP) { atomicAdd(&(bar)[XB_TMO], 1u); break; } } } } while (0)
; __device__ __forceinline__ void xcd_barrier(const XcdBarrier& b) {
;     ...
;             else XB_SPIN(xb_ld(&bar[XB_TOPGEN]) == tg, bar);
.LBB0_1929:
	s_and_b32 s14, s3, 0xff
	s_mov_b64 s[28:29], -1
	s_cmp_lg_u32 s14, 0
	s_mov_b64 s[38:39], -1
	s_nop 0
	s_cbranch_scc1 .LBB0_1932
	global_load_dword v2, v0, s[10:11] sc1
	s_waitcnt vmcnt(0)
	v_cmp_eq_u32_e32 vcc, 0, v2
	s_cbranch_vccnz .LBB0_1934
	s_mov_b64 s[38:39], 0
	s_mov_b64 s[36:37], -1

; __device__ __forceinline__ unsigned xb_ld(unsigned* p)              { return __hip_atomic_load(p, __ATOMIC_RELAXED, __HIP_MEMORY_SCOPE_AGENT); }
; #define XB_SPIN(cond, bar) do { unsigned _sp = 0; while (cond) { __builtin_amdgcn_s_sleep(1); \
;     if ((++_sp & 255u) == 0u) { if (xb_ld(&(bar)[XB_TMO])) break; if (_sp > XB_SPIN_CAP) { atomicAdd(&(bar)[XB_TMO], 1u); break; } } } } while (0)
; __device__ __forceinline__ void xcd_barrier(const XcdBarrier& b) {
;     ...
;             XB_SPIN(xb_ld(&bar[XB_XGEN(b.x)]) == gen, bar);
.LBB0_1946:
	s_and_b32 s14, s3, 0xff
	s_cmp_lg_u32 s14, 0
	s_mov_b64 s[36:37], -1
	s_nop 0
	s_cbranch_scc1 .LBB0_1949
	global_load_dword v1, v0, s[10:11] sc1
	s_waitcnt vmcnt(0)
	v_cmp_eq_u32_e32 vcc, 0, v1
	s_cbranch_vccnz .LBB0_1951
	s_mov_b64 s[36:37], 0
	s_mov_b64 s[28:29], -1

; __device__ __forceinline__ unsigned xb_ld(unsigned* p)              { return __hip_atomic_load(p, __ATOMIC_RELAXED, __HIP_MEMORY_SCOPE_AGENT); }
; __device__ __forceinline__ void xcd_barrier_complete(unsigned* bar, unsigned x, unsigned& nloc, unsigned& nx) {
;     ...
;     for (;;) {
;         sum = 0u; cnt = 0u; mine = 0u;
; #pragma unroll
;         for (unsigned j = 0; j < 16; ++j) { const unsigned c = xb_ld(&bar[XB_XCNT(j)]); sum += c; cnt += (c > 0u) ? 1u : 0u; mine = (j == x) ? c : mine; }
;         if (sum == G) break;
;         __builtin_amdgcn_s_sleep(1);
;         if ((++sp & 255u) == 0u) { if (xb_ld(&bar[XB_TMO])) break; if (sp > XB_SPIN_CAP) { atomicAdd(&bar[XB_TMO], 1u); break; } }
;     }
.LBB0_2005:
	global_load_dword v15, v16, s[4:5] sc1
	global_load_dword v0, v16, s[6:7] sc1
	global_load_dword v1, v16, s[8:9] sc1
	global_load_dword v2, v16, s[10:11] sc1
	global_load_dword v3, v16, s[12:13] sc1
	global_load_dword v4, v16, s[14:15] sc1
	global_load_dword v5, v16, s[16:17] sc1
	global_load_dword v6, v16, s[20:21] sc1
	global_load_dword v7, v16, s[24:25] sc1
	global_load_dword v8, v16, s[26:27] sc1
	global_load_dword v9, v16, s[28:29] sc1
	global_load_dword v10, v16, s[36:37] sc1
	global_load_dword v11, v16, s[38:39] sc1
	global_load_dword v12, v16, s[40:41] sc1
	global_load_dword v13, v16, s[42:43] sc1
	global_load_dword v14, v16, s[44:45] sc1
	s_mov_b64 s[46:47], -1
	s_mov_b64 s[48:49], -1
	s_waitcnt vmcnt(14)
	v_add_u32_e32 v17, v0, v15
	s_waitcnt vmcnt(13)
	v_add_u32_e32 v17, v17, v1
	s_waitcnt vmcnt(12)
	v_add_u32_e32 v17, v17, v2
	s_waitcnt vmcnt(11)
	v_add_u32_e32 v17, v17, v3
	s_waitcnt vmcnt(10)
	v_add_u32_e32 v17, v17, v4
	s_waitcnt vmcnt(9)
	v_add_u32_e32 v17, v17, v5
	s_waitcnt vmcnt(8)
	v_add_u32_e32 v17, v17, v6
	s_waitcnt vmcnt(7)
	v_add_u32_e32 v17, v17, v7
	s_waitcnt vmcnt(6)
	v_add_u32_e32 v17, v17, v8
	s_waitcnt vmcnt(5)
	v_add_u32_e32 v17, v17, v9
	s_waitcnt vmcnt(4)
	v_add_u32_e32 v17, v17, v10
	s_waitcnt vmcnt(3)
	v_add_u32_e32 v17, v17, v11
	s_waitcnt vmcnt(2)
	v_add_u32_e32 v17, v17, v12
	s_waitcnt vmcnt(1)
	v_add_u32_e32 v17, v17, v13
	s_waitcnt vmcnt(0)
	v_add_u32_e32 v17, v17, v14
	v_cmp_eq_u32_e32 vcc, s33, v17
	s_cbranch_vccnz .LBB0_2004
	s_and_b32 s34, s19, 0xff
	s_cmp_eq_u32 s34, 0
	s_mov_b64 s[50:51], -1
	s_nop 0
	s_cbranch_scc0 .LBB0_2009
	global_load_dword v17, v16, s[2:3] sc1
	s_waitcnt vmcnt(0)
	v_cmp_eq_u32_e32 vcc, 0, v17
	s_cbranch_vccnz .LBB0_2011
	s_mov_b64 s[50:51], 0

.LBB0_2023:
	s_and_b32 s20, s19, 0xff
	s_mov_b64 s[16:17], -1
	s_cmp_lg_u32 s20, 0
	s_mov_b64 s[24:25], -1
	s_nop 0
	s_cbranch_scc1 .LBB0_2026
	global_load_dword v2, v0, s[8:9] sc1
	s_waitcnt vmcnt(0)
	v_cmp_eq_u32_e32 vcc, 0, v2
	s_cbranch_vccnz .LBB0_2028
	s_mov_b64 s[24:25], 0
	s_mov_b64 s[20:21], -1

.LBB0_2040:
	s_and_b32 s16, s19, 0xff
	s_cmp_lg_u32 s16, 0
	s_mov_b64 s[20:21], -1
	s_nop 0
	s_cbranch_scc1 .LBB0_2043
	global_load_dword v1, v0, s[8:9] sc1
	s_waitcnt vmcnt(0)
	v_cmp_eq_u32_e32 vcc, 0, v1
	s_cbranch_vccnz .LBB0_2045
	s_mov_b64 s[20:21], 0
	s_mov_b64 s[16:17], -1
